# hand-written RWKV scan unit: 4 compute waves x 2 rows/lane lean step, in-place LDS reload 2 steps ahead, lean staging waves with 2-chunk-deep global prefetch, static prio
# speedup vs baseline: 1.0075x; 1.0075x over previous
.LBB0_235:
	v_readlane_b32 s12, v254, 35
	s_cmp_gt_i32 s12, 8
	s_mov_b64 s[24:25], -1
	s_cbranch_scc0 .LBB0_636
	v_writelane_b32 v254, s62, 38
	s_waitcnt vmcnt(0)
	v_mbcnt_lo_u32_b32 v47, -1, 0
	v_mbcnt_hi_u32_b32 v47, -1, v47
	v_readlane_b32 s2, v254, 29
	s_cmpk_gt_i32 s2, 0xef
	s_cbranch_scc1 .LBB0_529
	v_readlane_b32 s2, v254, 38
	v_ashrrev_i32_e32 v6, 1, v47
	s_lshl_b32 s12, s2, 1
	v_and_b32_e32 v2, -8, v6
	s_mul_i32 s24, s2, 0x3000
	s_mul_hi_i32 s25, s12, 0x1800
	v_or_b32_e32 v4, 1, v2
	v_readlane_b32 s27, v254, 30
	v_writelane_b32 v254, s24, 51
	v_ashrrev_i32_e32 v5, 31, v4
	s_mulk_i32 s2, 0x300
	v_writelane_b32 v254, s25, 52
	s_or_b32 s24, s12, 1
	v_lshlrev_b64 v[54:55], 8, v[4:5]
	v_or_b32_e32 v4, 2, v2
	v_writelane_b32 v254, s2, 53
	s_mul_hi_i32 s13, s24, 0x1800
	s_mul_i32 s12, s24, 0x1800
	s_lshl_b32 s25, s27, 4
	v_ashrrev_i32_e32 v5, 31, v4
	v_writelane_b32 v254, s12, 54
	s_and_b32 s26, s25, 48
	v_lshlrev_b64 v[56:57], 8, v[4:5]
	v_or_b32_e32 v4, 3, v2
	v_writelane_b32 v254, s13, 55
	s_mul_i32 s2, s24, 0x180
	s_cmp_lt_u32 s27, 4
	s_movk_i32 s12, 0xc8
	v_ashrrev_i32_e32 v5, 31, v4
	v_writelane_b32 v254, s2, 56
	s_cselect_b32 s2, s12, 0xd8
	s_movk_i32 s12, 0xd0
	v_ashrrev_i32_e32 v3, 31, v2
	v_lshlrev_b64 v[58:59], 8, v[4:5]
	v_or_b32_e32 v4, 4, v2
	v_writelane_b32 v254, s2, 57
	s_cselect_b32 s2, s12, 0xe0
	v_lshlrev_b64 v[50:51], 8, v[2:3]
	s_mov_b64 s[12:13], 0x2000
	v_ashrrev_i32_e32 v5, 31, v4
	v_lshl_add_u64 v[52:53], v[50:51], 0, s[12:13]
	v_lshlrev_b64 v[60:61], 8, v[4:5]
	v_or_b32_e32 v4, 5, v2
	v_or_b32_e32 v2, 6, v2
	s_mov_b64 s[12:13], 0x2100
	v_ashrrev_i32_e32 v3, 31, v2
	v_lshl_add_u64 v[68:69], v[50:51], 0, s[12:13]
	s_mov_b64 s[12:13], 0x2200
	v_lshlrev_b64 v[64:65], 8, v[2:3]
	v_or_b32_e32 v2, 7, v6
	v_lshl_add_u64 v[70:71], v[50:51], 0, s[12:13]
	s_mov_b64 s[12:13], 0x2300
	v_ashrrev_i32_e32 v3, 31, v2
	v_lshl_add_u64 v[72:73], v[50:51], 0, s[12:13]
	s_mov_b64 s[12:13], 0x2400
	v_lshl_add_u32 v49, s27, 6, v47
	v_lshlrev_b64 v[66:67], 8, v[2:3]
	v_lshl_add_u64 v[74:75], v[50:51], 0, s[12:13]
	s_mov_b64 s[12:13], 0x2500
	v_lshlrev_b32_e32 v2, 3, v47
	v_lshl_add_u64 v[76:77], v[50:51], 0, s[12:13]
	s_mov_b64 s[12:13], 0x2600
	v_and_b32_e32 v82, 56, v2
	v_ashrrev_i32_e32 v2, 3, v49
	v_writelane_b32 v254, s2, 58
	v_ashrrev_i32_e32 v5, 31, v4
	v_lshl_add_u64 v[78:79], v[50:51], 0, s[12:13]
	s_mov_b64 s[12:13], 0x2700
	s_mul_i32 s2, s24, 6
	v_add_u32_e32 v83, -3, v2
	v_add_u32_e32 v3, 0x200, v49
	v_lshlrev_b64 v[62:63], 8, v[4:5]
	v_lshl_add_u64 v[80:81], v[50:51], 0, s[12:13]
	v_writelane_b32 v254, s2, 59
	v_cmp_gt_u32_e64 s[12:13], 64, v83
	v_ashrrev_i32_e32 v4, 3, v3
	v_add_u32_e32 v85, -3, v4
	v_writelane_b32 v254, s12, 60
	v_add_u32_e32 v87, 0xc0, v2
	s_movk_i32 s2, 0x100
	v_writelane_b32 v254, s13, 61
	v_cmp_gt_u32_e64 s[12:13], 64, v85
	v_add_u32_e32 v89, 0xc0, v4
	s_and_b32 s60, s25, 0xffffc0
	v_writelane_b32 v254, s12, 62
	v_ashrrev_i32_e32 v2, 4, v47
	v_and_b32_e32 v0, 15, v47
	v_writelane_b32 v254, s13, 63
	v_cmp_gt_u32_e64 s[12:13], s2, v87
	v_or_b32_e32 v48, s26, v0
	v_cmp_gt_u32_e64 s[74:75], 8, v0
	v_writelane_b32 v255, s12, 0
	v_and_b32_e32 v46, 63, v47
	s_nop 0
	v_writelane_b32 v255, s13, 1
	v_cmp_gt_u32_e64 s[12:13], s2, v89
	s_nop 1
	v_writelane_b32 v255, s12, 2
	s_nop 1
	v_writelane_b32 v255, s13, 3
	s_lshl_b32 s12, s26, 2
	s_add_i32 s13, s12, 0
	s_cmp_lt_i32 s27, 2
	s_cselect_b64 s[46:47], -1, 0
	s_cmp_eq_u32 s27, 0
	s_cselect_b64 s[48:49], -1, 0
	s_lshl_b32 s12, s27, 15
	s_add_i32 s61, s12, 0
	s_lshl_b32 s12, s27, 14
	s_add_i32 s64, s12, 0
	s_lshl_b32 s12, s27, 3
	s_and_b32 s12, s12, 24
	v_add_u32_e32 v91, s12, v2
	v_add_u32_e32 v2, 0xffffff00, v49
	v_mul_hi_i32 v4, v2, s11
	v_lshrrev_b32_e32 v5, 31, v4
	v_ashrrev_i32_e32 v4, 3, v4
	v_add_u32_e32 v93, v4, v5
	s_movk_i32 s12, 0x30ff
	v_mul_lo_u32 v4, v93, 48
	v_cmp_lt_i32_e32 vcc, s12, v49
	v_sub_u32_e32 v4, v2, v4
	s_movk_i32 s12, 0x2fff
	v_cndmask_b32_e32 v5, v208, v209, vcc
	v_sub_u32_e32 v95, v5, v93
	v_lshlrev_b32_e32 v5, 3, v4
	v_and_b32_e32 v84, 56, v5
	v_mul_hi_i32 v5, v49, s11
	v_lshrrev_b32_e32 v6, 31, v5
	v_ashrrev_i32_e32 v5, 3, v5
	v_add_u32_e32 v101, v5, v6
	v_mul_lo_u32 v5, v101, 48
	v_cmp_lt_i32_e32 vcc, s12, v49
	v_sub_u32_e32 v5, v49, v5
	s_movk_i32 s12, 0x2eff
	v_cndmask_b32_e32 v6, v208, v209, vcc
	v_sub_u32_e32 v105, v6, v101
	v_lshlrev_b32_e32 v6, 3, v5
	v_and_b32_e32 v86, 56, v6
	v_add_u32_e32 v6, 0x100, v49
	v_mul_hi_i32 v7, v6, s11
	v_lshrrev_b32_e32 v8, 31, v7
	v_ashrrev_i32_e32 v7, 3, v7
	v_add_u32_e32 v113, v7, v8
	v_mul_lo_u32 v7, v113, 48
	v_cmp_lt_i32_e32 vcc, s12, v49
	v_sub_u32_e32 v6, v6, v7
	s_movk_i32 s12, 0x2dff
	v_cndmask_b32_e32 v7, v208, v209, vcc
	v_sub_u32_e32 v117, v7, v113
	v_lshlrev_b32_e32 v7, 3, v6
	v_and_b32_e32 v88, 56, v7
	v_mul_hi_i32 v7, v3, s11
	v_lshrrev_b32_e32 v8, 31, v7
	v_ashrrev_i32_e32 v7, 3, v7
	v_add_u32_e32 v144, v7, v8
	v_mul_lo_u32 v7, v144, 48
	v_cmp_lt_i32_e32 vcc, s12, v49
	v_sub_u32_e32 v3, v3, v7
	s_movk_i32 s12, 0x2cff
	v_cndmask_b32_e32 v7, v208, v209, vcc
	v_sub_u32_e32 v145, v7, v144
	v_lshlrev_b32_e32 v7, 3, v3
	v_and_b32_e32 v90, 56, v7
	v_add_u32_e32 v7, 0x300, v49
	v_mul_hi_i32 v8, v7, s11
	v_lshrrev_b32_e32 v9, 31, v8
	v_ashrrev_i32_e32 v8, 3, v8
	v_add_u32_e32 v147, v8, v9
	v_mul_lo_u32 v8, v147, 48
	v_cmp_lt_i32_e32 vcc, s12, v49
	v_sub_u32_e32 v7, v7, v8
	s_add_i32 s64, s64, 0x10000
	v_cndmask_b32_e32 v8, v208, v209, vcc
	v_sub_u32_e32 v148, v8, v147
	v_lshlrev_b32_e32 v8, 3, v7
	v_and_b32_e32 v92, 56, v8
	v_add_u32_e32 v8, 0x400, v49
	v_mul_hi_i32 v9, v8, s11
	s_cmp_gt_i32 s27, 3
	v_lshrrev_b32_e32 v10, 31, v9
	v_ashrrev_i32_e32 v9, 3, v9
	s_cselect_b64 s[24:25], -1, 0
	v_add_u32_e32 v150, v9, v10
	s_movk_i32 s12, 0x2bff
	v_writelane_b32 v255, s24, 4
	v_mul_lo_u32 v9, v150, 48
	v_cmp_lt_i32_e32 vcc, s12, v49
	v_writelane_b32 v255, s25, 5
	v_cmp_lt_u32_e64 s[24:25], 7, v4
	v_sub_u32_e32 v8, v8, v9
	v_cndmask_b32_e32 v9, v208, v209, vcc
	v_cmp_gt_u32_e64 s[50:51], 8, v4
	v_writelane_b32 v254, s24, 43
	v_ashrrev_i32_e32 v97, 3, v4
	v_sub_u32_e32 v151, v9, v150
	v_lshlrev_b32_e32 v9, 3, v8
	v_lshlrev_b32_e32 v4, 5, v4
	v_writelane_b32 v254, s25, 44
	v_cmp_lt_u32_e64 s[24:25], 7, v5
	v_and_b32_e32 v94, 56, v9
	v_and_b32_e32 v4, 0xffffff00, v4
	v_lshlrev_b32_e32 v9, 2, v84
	v_writelane_b32 v254, s24, 45
	v_add3_u32 v96, 0, v4, v9
	v_lshlrev_b32_e32 v4, 5, v5
	v_cmp_gt_u32_e64 s[54:55], 8, v5
	v_writelane_b32 v254, s25, 46
	v_ashrrev_i32_e32 v109, 3, v5
	v_cmp_lt_u32_e64 s[24:25], 7, v6
	v_and_b32_e32 v4, 0xffffff00, v4
	v_lshlrev_b32_e32 v5, 2, v86
	v_writelane_b32 v254, s24, 47
	v_add3_u32 v100, 0, v4, v5
	v_lshlrev_b32_e32 v4, 5, v6
	v_writelane_b32 v254, s25, 48
	v_cmp_gt_u32_e64 s[62:63], 8, v3
	v_cmp_lt_u32_e64 s[24:25], 7, v3
	v_ashrrev_i32_e32 v146, 3, v3
	v_and_b32_e32 v4, 0xffffff00, v4
	v_lshlrev_b32_e32 v5, 2, v88
	v_lshlrev_b32_e32 v3, 5, v3
	v_writelane_b32 v254, s24, 49
	v_add3_u32 v104, 0, v4, v5
	v_and_b32_e32 v3, 0xffffff00, v3
	v_lshlrev_b32_e32 v4, 2, v90
	v_writelane_b32 v254, s25, 50
	v_cmp_lt_u32_e64 s[24:25], 7, v7
	v_add3_u32 v108, 0, v3, v4
	v_lshlrev_b32_e32 v3, 5, v7
	v_writelane_b32 v255, s24, 6
	v_and_b32_e32 v3, 0xffffff00, v3
	v_lshlrev_b32_e32 v4, 2, v92
	v_writelane_b32 v255, s25, 7
	v_cmp_lt_u32_e64 s[24:25], 7, v8
	v_add3_u32 v112, 0, v3, v4
	v_lshlrev_b32_e32 v3, 5, v8
	v_writelane_b32 v255, s24, 8
	v_and_b32_e32 v3, 0xffffff00, v3
	v_lshlrev_b32_e32 v4, 2, v94
	v_writelane_b32 v255, s25, 9
	v_mad_u64_u32 v[102:103], s[24:25], v101, s89, v[100:101]
	v_add3_u32 v116, 0, v3, v4
	v_and_b32_e32 v3, 4, v47
	v_cmp_eq_u32_e64 s[76:77], 0, v3
	v_and_b32_e32 v3, 1, v47
	v_ashrrev_i32_e32 v103, 3, v2
	s_movk_i32 s12, 0xf01f
	v_mad_u64_u32 v[110:111], s[24:25], v144, s89, v[108:109]
	v_cmp_lt_i32_e32 vcc, s12, v103
	v_cmp_eq_u32_e64 s[80:81], 0, v3
	v_lshlrev_b32_e32 v3, 2, v47
	s_cmp_lt_i32 s27, 4
	v_mad_u64_u32 v[98:99], s[24:25], v93, s89, v[96:97]
	v_mad_u64_u32 v[114:115], s[24:25], v147, s89, v[112:113]
	v_and_b32_e32 v4, 2, v47
	v_cndmask_b32_e32 v2, v208, v209, vcc
	v_and_b32_e32 v120, 28, v3
	v_add_u32_e32 v111, 0x10e0, v103
	s_cselect_b64 s[42:43], -1, 0
	v_mad_u64_u32 v[106:107], s[24:25], v113, s89, v[104:105]
	v_mad_u64_u32 v[118:119], s[24:25], v150, s89, v[116:117]
	v_lshlrev_b32_e32 v99, 2, v0
	v_cmp_eq_u32_e64 s[78:79], 0, v4
	v_lshlrev_b32_e32 v0, 7, v0
	s_add_i32 s65, 0, 0x18000
	v_lshlrev_b32_e32 v3, 7, v103
	v_lshlrev_b32_e32 v4, 2, v120
	v_sub_u32_e32 v115, v2, v111
	v_readlane_b32 s2, v254, 4
	v_lshlrev_b32_e32 v2, 2, v91
	v_cmp_gt_u32_e64 s[58:59], 8, v6
	v_ashrrev_i32_e32 v121, 3, v6
	v_cmp_gt_u32_e64 s[66:67], 8, v7
	v_ashrrev_i32_e32 v149, 3, v7
	v_cmp_gt_u32_e64 s[70:71], 8, v8
	v_ashrrev_i32_e32 v152, 3, v8
	v_add3_u32 v107, s65, v3, v4
	v_add3_u32 v119, s2, v3, v4
	v_add3_u32 v153, s65, v0, v2
	v_readlane_b32 s12, v254, 29
	s_branch .LBB0_240
.LBB0_239:
	s_add_i32 s12, s12, s90
	s_cmpk_gt_i32 s12, 0xef
	s_barrier
	s_cbranch_scc1 .LBB0_529

.LBB0_297:
	s_and_b64 vcc, exec, s[24:25]
	s_cbranch_vccz .LBB0_239
	v_mbcnt_lo_u32_b32 v0, -1, 0
	v_mbcnt_hi_u32_b32 v0, -1, v0
	v_readlane_b32 s34, v254, 30
	s_lshr_b32 s26, s12, 1
	s_and_b32 s52, s12, 1
	s_mul_hi_u32 s53, s26, 0xaaaaaaab
	s_lshr_b32 s53, s53, 3
	s_mul_i32 s27, s53, 12
	s_sub_u32 s27, s26, s27
	s_lshr_b32 s24, s27, 1
	s_and_b32 s35, s27, 1
	s_add_i32 s26, s38, -1
	s_lshr_b32 s26, s26, 4
	s_and_b32 s36, s26, 1
	s_cmp_eq_u32 s35, 0
	s_cselect_b32 s37, 1, -1
	s_lshl_b32 s44, s53, 8
	s_add_u32 s44, s44, 0x8000
	s_lshl_b32 s45, s53, 12
	s_mov_b32 s2, 0
	s_cmp_gt_u32 s34, 3
	s_cbranch_scc1 .Lrc_setup_stage
	s_setprio 3
	v_and_b32_e32 v176, 15, v0
	v_lshrrev_b32_e32 v177, 4, v0
	v_lshl_add_u32 v178, s34, 3, v177
	v_lshlrev_b32_e32 v42, 4, v176
	v_lshl_add_u32 v179, s52, 5, v178
	v_lshlrev_b32_e32 v43, 2, v179
	v_add_u32_e32 v43, 0x500, v43
	v_mul_u32_u24_e32 v44, 144, v176
	v_lshl_add_u32 v44, v178, 2, v44
	v_add_u32_e32 v44, 0x18000, v44
	v_and_b32_e32 v179, 8, v176
	v_cmp_ne_u32_e64 s[56:57], 0, v179
	v_and_b32_e32 v179, 4, v176
	v_cmp_ne_u32_e64 s[82:83], 0, v179
	v_and_b32_e32 v179, 2, v176
	v_cmp_ne_u32_e64 s[84:85], 0, v179
	v_and_b32_e32 v179, 1, v176
	v_cmp_ne_u32_e64 s[88:89], 0, v179
	v_mov_b32_e32 v2, 0
	v_mov_b32_e32 v3, 0
	v_mov_b32_e32 v4, 0
	v_mov_b32_e32 v5, 0
	v_mov_b32_e32 v6, 0
	v_mov_b32_e32 v7, 0
	v_mov_b32_e32 v8, 0
	v_mov_b32_e32 v9, 0
	s_branch .Lrc_setup_done
.Lrc_setup_stage:
	s_sub_u32 s26, s34, 4
	v_lshl_add_u32 v127, s26, 6, v0
	v_lshrrev_b32_e32 v128, 3, v127
	v_and_b32_e32 v129, 7, v127
	v_mul_lo_u32 v124, v128, s37
	v_mul_u32_u24_e32 v125, 144, v128
	v_lshl_add_u32 v125, v129, 4, v125
	v_add_u32_e32 v125, 0x1a000, v125
	s_mul_i32 s26, s35, 0x300
	s_lshl_b32 s27, s24, 7
	s_add_u32 s26, s26, s27
	s_lshl_b32 s27, s52, 6
	s_add_u32 s26, s26, s27
	s_add_u32 s26, s26, 0x600
	v_lshl_add_u32 v126, v129, 3, s26
	v_mul_u32_u24_e32 v123, 0x600, v128
	v_lshl_add_u32 v123, v129, 5, v123
	s_mul_i32 s29, s53, 0x330000
	s_lshl_b32 s27, s24, 7
	s_add_u32 s29, s29, s27
	s_mul_i32 s30, s37, 0x300
	v_mul_lo_u32 v122, v128, s30
	v_lshl_add_u32 v122, v129, 4, v122
	v_add_u32_e32 v122, s29, v122
	s_add_u32 s26, s35, 7
	s_mul_i32 s92, s26, 0x1980000
	s_add_u32 s26, s35, 5
	s_mul_i32 s93, s26, 0x1980000
	s_add_u32 s26, s35, 3
	s_mul_i32 s94, s26, 0x1980000
	s_lshl_b32 s26, s2, 5
	s_movk_i32 s27, 0xff
	s_cmp_lt_u32 s26, 0x100
	s_cselect_b32 s27, s27, 0x11ff
	s_sub_u32 s27, s27, s26
	s_cmp_eq_u32 s35, 0
	s_cselect_b32 s29, s26, s27
	s_mul_i32 s29, s29, 0x300
	v_add_u32_e32 v127, s29, v122
	v_add_u32_e32 v128, s92, v127
	global_load_dwordx4 v[2:5], v128, s[18:19]
	v_add_u32_e32 v128, s93, v127
	global_load_dwordx4 v[6:9], v128, s[18:19]
	v_add_u32_e32 v128, s94, v127
	global_load_dwordx4 v[10:13], v128, s[18:19]
	v_add_u32_e32 v128, 0x3300000, v127
	global_load_dwordx4 v[14:17], v128, s[18:19]
	v_mov_b32_e32 v128, v127
	global_load_dwordx4 v[18:21], v128, s[18:19]
	v_add_u32_e32 v128, 0x1980000, v127
	global_load_dwordx4 v[22:25], v128, s[18:19]
	s_mov_b32 s25, 0
	s_waitcnt vmcnt(0)
	v_add_u32_e32 v129, s25, v123
	v_lshlrev_b32_e32 v26, 16, v2
	v_and_b32_e32 v27, 0xffff0000, v2
	v_lshlrev_b32_e32 v28, 16, v3
	v_and_b32_e32 v29, 0xffff0000, v3
	v_lshlrev_b32_e32 v30, 16, v4
	v_and_b32_e32 v31, 0xffff0000, v4
	v_lshlrev_b32_e32 v32, 16, v5
	v_and_b32_e32 v33, 0xffff0000, v5
	v_sub_f32_e32 v26, 1.0, v26
	v_sub_f32_e32 v27, 1.0, v27
	v_sub_f32_e32 v28, 1.0, v28
	v_sub_f32_e32 v29, 1.0, v29
	v_sub_f32_e32 v30, 1.0, v30
	v_sub_f32_e32 v31, 1.0, v31
	v_sub_f32_e32 v32, 1.0, v32
	v_sub_f32_e32 v33, 1.0, v33
	ds_write_b128 v129, v[26:29] offset:0
	ds_write_b128 v129, v[30:33] offset:16
	v_lshlrev_b32_e32 v34, 16, v6
	v_and_b32_e32 v35, 0xffff0000, v6
	v_lshlrev_b32_e32 v36, 16, v7
	v_and_b32_e32 v37, 0xffff0000, v7
	v_lshlrev_b32_e32 v38, 16, v8
	v_and_b32_e32 v39, 0xffff0000, v8
	v_lshlrev_b32_e32 v40, 16, v9
	v_and_b32_e32 v41, 0xffff0000, v9
	ds_write_b128 v129, v[34:37] offset:256
	ds_write_b128 v129, v[38:41] offset:272
	v_lshlrev_b32_e32 v26, 16, v10
	v_and_b32_e32 v27, 0xffff0000, v10
	v_lshlrev_b32_e32 v28, 16, v11
	v_and_b32_e32 v29, 0xffff0000, v11
	v_lshlrev_b32_e32 v30, 16, v12
	v_and_b32_e32 v31, 0xffff0000, v12
	v_lshlrev_b32_e32 v32, 16, v13
	v_and_b32_e32 v33, 0xffff0000, v13
	ds_write_b128 v129, v[26:29] offset:512
	ds_write_b128 v129, v[30:33] offset:528
	v_lshlrev_b32_e32 v34, 16, v14
	v_and_b32_e32 v35, 0xffff0000, v14
	v_lshlrev_b32_e32 v36, 16, v15
	v_and_b32_e32 v37, 0xffff0000, v15
	v_lshlrev_b32_e32 v38, 16, v16
	v_and_b32_e32 v39, 0xffff0000, v16
	v_lshlrev_b32_e32 v40, 16, v17
	v_and_b32_e32 v41, 0xffff0000, v17
	ds_write_b128 v129, v[34:37] offset:768
	ds_write_b128 v129, v[38:41] offset:784
	v_lshlrev_b32_e32 v26, 16, v18
	v_and_b32_e32 v27, 0xffff0000, v18
	v_lshlrev_b32_e32 v28, 16, v19
	v_and_b32_e32 v29, 0xffff0000, v19
	v_lshlrev_b32_e32 v30, 16, v20
	v_and_b32_e32 v31, 0xffff0000, v20
	v_lshlrev_b32_e32 v32, 16, v21
	v_and_b32_e32 v33, 0xffff0000, v21
	ds_write_b128 v129, v[26:29] offset:1024
	ds_write_b128 v129, v[30:33] offset:1040
	v_lshlrev_b32_e32 v34, 16, v22
	v_and_b32_e32 v35, 0xffff0000, v22
	v_lshlrev_b32_e32 v36, 16, v23
	v_and_b32_e32 v37, 0xffff0000, v23
	v_lshlrev_b32_e32 v38, 16, v24
	v_and_b32_e32 v39, 0xffff0000, v24
	v_lshlrev_b32_e32 v40, 16, v25
	v_and_b32_e32 v41, 0xffff0000, v25
	ds_write_b128 v129, v[34:37] offset:1280
	ds_write_b128 v129, v[38:41] offset:1296
	s_mov_b32 s25, 0xc000
	s_mov_b32 s30, 1
	s_lshl_b32 s26, s30, 5
	s_movk_i32 s27, 0xff
	s_cmp_lt_u32 s26, 0x100
	s_cselect_b32 s27, s27, 0x11ff
	s_sub_u32 s27, s27, s26
	s_cmp_eq_u32 s35, 0
	s_cselect_b32 s29, s26, s27
	s_mul_i32 s29, s29, 0x300
	v_add_u32_e32 v127, s29, v122
	v_add_u32_e32 v128, s92, v127
	global_load_dwordx4 v[154:157], v128, s[18:19]
	v_add_u32_e32 v128, s93, v127
	global_load_dwordx4 v[158:161], v128, s[18:19]
	v_add_u32_e32 v128, s94, v127
	global_load_dwordx4 v[162:165], v128, s[18:19]
	v_add_u32_e32 v128, 0x3300000, v127
	global_load_dwordx4 v[166:169], v128, s[18:19]
	v_mov_b32_e32 v128, v127
	global_load_dwordx4 v[170:173], v128, s[18:19]
	v_add_u32_e32 v128, 0x1980000, v127
	global_load_dwordx4 v[174:177], v128, s[18:19]

.Lrc_chunk:
	s_cmp_gt_u32 s34, 3
	s_cbranch_scc1 .Lrc_stage
	ds_read_b128 v[134:137], v42 offset:768
	ds_read_b128 v[130:133], v42 offset:512
	ds_read_b32 v142, v43 offset:0
	ds_read_b32 v143, v43 offset:16
	ds_read_b128 v[122:125], v42 offset:0
	ds_read_b128 v[126:129], v42 offset:256
	ds_read_b128 v[138:141], v42 offset:1024
	ds_read_b128 v[166:169], v42 offset:2304
	ds_read_b128 v[162:165], v42 offset:2048
	ds_read_b32 v174, v43 offset:1536
	ds_read_b32 v175, v43 offset:1552
	ds_read_b128 v[154:157], v42 offset:1536
	ds_read_b128 v[158:161], v42 offset:1792
	ds_read_b128 v[170:173], v42 offset:2560
	s_waitcnt lgkmcnt(7)
	v_pk_mul_f32 v[176:177], v[2:3], v[134:135]
	v_pk_mul_f32 v[178:179], v[6:7], v[134:135]
	v_pk_fma_f32 v[176:177], v[4:5], v[136:137], v[176:177]
	v_pk_fma_f32 v[178:179], v[8:9], v[136:137], v[178:179]
	v_pk_mul_f32 v[180:181], v[130:131], v[142:143] op_sel_hi:[1,0]
	v_add_f32_e32 v198, v176, v177
	v_pk_mul_f32 v[190:191], v[130:131], v[142:143] op_sel:[0,1] op_sel_hi:[1,1]
	v_add_f32_e32 v200, v178, v179
	v_pk_mul_f32 v[188:189], v[132:133], v[142:143] op_sel_hi:[1,0]
	v_add_f32_dpp v198, v198, v198 quad_perm:[1,0,3,2] row_mask:0xf bank_mask:0xf bound_ctrl:1
	v_pk_mul_f32 v[192:193], v[132:133], v[142:143] op_sel:[0,1] op_sel_hi:[1,1]
	v_add_f32_dpp v200, v200, v200 quad_perm:[1,0,3,2] row_mask:0xf bank_mask:0xf bound_ctrl:1
	v_pk_fma_f32 v[2:3], v[2:3], v[122:123], v[180:181]
	v_add_f32_dpp v198, v198, v198 quad_perm:[2,3,0,1] row_mask:0xf bank_mask:0xf bound_ctrl:1
	v_pk_fma_f32 v[6:7], v[6:7], v[122:123], v[190:191]
	v_add_f32_dpp v200, v200, v200 quad_perm:[2,3,0,1] row_mask:0xf bank_mask:0xf bound_ctrl:1
	v_pk_fma_f32 v[4:5], v[4:5], v[124:125], v[188:189]
	v_add_f32_dpp v198, v198, v198 row_half_mirror row_mask:0xf bank_mask:0xf bound_ctrl:1
	v_pk_fma_f32 v[8:9], v[8:9], v[124:125], v[192:193]
	v_add_f32_dpp v200, v200, v200 row_half_mirror row_mask:0xf bank_mask:0xf bound_ctrl:1
	ds_read_b128 v[134:137], v42 offset:3840
	v_add_f32_dpp v198, v198, v198 row_mirror row_mask:0xf bank_mask:0xf bound_ctrl:1
	ds_read_b128 v[130:133], v42 offset:3584
	v_add_f32_dpp v200, v200, v200 row_mirror row_mask:0xf bank_mask:0xf bound_ctrl:1
	ds_read_b32 v142, v43 offset:3072
	ds_read_b32 v143, v43 offset:3088
	v_pk_fma_f32 v[2:3], v[126:127], v[198:199], v[2:3] op_sel_hi:[1,0,1] neg_lo:[0,1,0] neg_hi:[0,1,0]
	v_pk_fma_f32 v[4:5], v[128:129], v[198:199], v[4:5] op_sel_hi:[1,0,1] neg_lo:[0,1,0] neg_hi:[0,1,0]
	v_pk_fma_f32 v[6:7], v[126:127], v[200:201], v[6:7] op_sel_hi:[1,0,1] neg_lo:[0,1,0] neg_hi:[0,1,0]
	v_pk_fma_f32 v[8:9], v[128:129], v[200:201], v[8:9] op_sel_hi:[1,0,1] neg_lo:[0,1,0] neg_hi:[0,1,0]
	ds_read_b128 v[122:125], v42 offset:3072
	v_pk_mul_f32 v[194:195], v[140:141], v[4:5]
	v_pk_mul_f32 v[196:197], v[140:141], v[8:9]
	ds_read_b128 v[126:129], v42 offset:3328
	v_pk_fma_f32 v[194:195], v[138:139], v[2:3], v[194:195]
	v_pk_fma_f32 v[196:197], v[138:139], v[6:7], v[196:197]
	ds_read_b128 v[138:141], v42 offset:4096
	v_add_f32_e32 v10, v194, v195
	v_add_f32_e32 v26, v196, v197
	s_waitcnt lgkmcnt(7)
	v_pk_mul_f32 v[176:177], v[2:3], v[166:167]
	v_pk_mul_f32 v[178:179], v[6:7], v[166:167]
	v_pk_fma_f32 v[176:177], v[4:5], v[168:169], v[176:177]
	v_pk_fma_f32 v[178:179], v[8:9], v[168:169], v[178:179]
	v_pk_mul_f32 v[180:181], v[162:163], v[174:175] op_sel_hi:[1,0]
	v_add_f32_e32 v198, v176, v177
	v_pk_mul_f32 v[190:191], v[162:163], v[174:175] op_sel:[0,1] op_sel_hi:[1,1]
	v_add_f32_e32 v200, v178, v179
	v_pk_mul_f32 v[188:189], v[164:165], v[174:175] op_sel_hi:[1,0]
	v_add_f32_dpp v198, v198, v198 quad_perm:[1,0,3,2] row_mask:0xf bank_mask:0xf bound_ctrl:1
	v_pk_mul_f32 v[192:193], v[164:165], v[174:175] op_sel:[0,1] op_sel_hi:[1,1]
	v_add_f32_dpp v200, v200, v200 quad_perm:[1,0,3,2] row_mask:0xf bank_mask:0xf bound_ctrl:1
	v_pk_fma_f32 v[2:3], v[2:3], v[154:155], v[180:181]
	v_add_f32_dpp v198, v198, v198 quad_perm:[2,3,0,1] row_mask:0xf bank_mask:0xf bound_ctrl:1
	v_pk_fma_f32 v[6:7], v[6:7], v[154:155], v[190:191]
	v_add_f32_dpp v200, v200, v200 quad_perm:[2,3,0,1] row_mask:0xf bank_mask:0xf bound_ctrl:1
	v_pk_fma_f32 v[4:5], v[4:5], v[156:157], v[188:189]
	v_add_f32_dpp v198, v198, v198 row_half_mirror row_mask:0xf bank_mask:0xf bound_ctrl:1
	v_pk_fma_f32 v[8:9], v[8:9], v[156:157], v[192:193]
	v_add_f32_dpp v200, v200, v200 row_half_mirror row_mask:0xf bank_mask:0xf bound_ctrl:1
	ds_read_b128 v[166:169], v42 offset:5376
	v_add_f32_dpp v198, v198, v198 row_mirror row_mask:0xf bank_mask:0xf bound_ctrl:1
	ds_read_b128 v[162:165], v42 offset:5120
	v_add_f32_dpp v200, v200, v200 row_mirror row_mask:0xf bank_mask:0xf bound_ctrl:1
	ds_read_b32 v174, v43 offset:4608
	ds_read_b32 v175, v43 offset:4624
	v_pk_fma_f32 v[2:3], v[158:159], v[198:199], v[2:3] op_sel_hi:[1,0,1] neg_lo:[0,1,0] neg_hi:[0,1,0]
	v_pk_fma_f32 v[4:5], v[160:161], v[198:199], v[4:5] op_sel_hi:[1,0,1] neg_lo:[0,1,0] neg_hi:[0,1,0]
	v_pk_fma_f32 v[6:7], v[158:159], v[200:201], v[6:7] op_sel_hi:[1,0,1] neg_lo:[0,1,0] neg_hi:[0,1,0]
	v_pk_fma_f32 v[8:9], v[160:161], v[200:201], v[8:9] op_sel_hi:[1,0,1] neg_lo:[0,1,0] neg_hi:[0,1,0]
	ds_read_b128 v[154:157], v42 offset:4608
	v_pk_mul_f32 v[194:195], v[172:173], v[4:5]
	v_pk_mul_f32 v[196:197], v[172:173], v[8:9]
	ds_read_b128 v[158:161], v42 offset:4864
	v_pk_fma_f32 v[194:195], v[170:171], v[2:3], v[194:195]
	v_pk_fma_f32 v[196:197], v[170:171], v[6:7], v[196:197]
	ds_read_b128 v[170:173], v42 offset:5632
	v_add_f32_e32 v11, v194, v195
	v_add_f32_e32 v27, v196, v197
	s_waitcnt lgkmcnt(7)
	v_pk_mul_f32 v[176:177], v[2:3], v[134:135]
	v_pk_mul_f32 v[178:179], v[6:7], v[134:135]
	v_pk_fma_f32 v[176:177], v[4:5], v[136:137], v[176:177]
	v_pk_fma_f32 v[178:179], v[8:9], v[136:137], v[178:179]
	v_pk_mul_f32 v[180:181], v[130:131], v[142:143] op_sel_hi:[1,0]
	v_add_f32_e32 v198, v176, v177
	v_pk_mul_f32 v[190:191], v[130:131], v[142:143] op_sel:[0,1] op_sel_hi:[1,1]
	v_add_f32_e32 v200, v178, v179
	v_pk_mul_f32 v[188:189], v[132:133], v[142:143] op_sel_hi:[1,0]
	v_add_f32_dpp v198, v198, v198 quad_perm:[1,0,3,2] row_mask:0xf bank_mask:0xf bound_ctrl:1
	v_pk_mul_f32 v[192:193], v[132:133], v[142:143] op_sel:[0,1] op_sel_hi:[1,1]
	v_add_f32_dpp v200, v200, v200 quad_perm:[1,0,3,2] row_mask:0xf bank_mask:0xf bound_ctrl:1
	v_pk_fma_f32 v[2:3], v[2:3], v[122:123], v[180:181]
	v_add_f32_dpp v198, v198, v198 quad_perm:[2,3,0,1] row_mask:0xf bank_mask:0xf bound_ctrl:1
	v_pk_fma_f32 v[6:7], v[6:7], v[122:123], v[190:191]
	v_add_f32_dpp v200, v200, v200 quad_perm:[2,3,0,1] row_mask:0xf bank_mask:0xf bound_ctrl:1
	v_pk_fma_f32 v[4:5], v[4:5], v[124:125], v[188:189]
	v_add_f32_dpp v198, v198, v198 row_half_mirror row_mask:0xf bank_mask:0xf bound_ctrl:1
	v_pk_fma_f32 v[8:9], v[8:9], v[124:125], v[192:193]
	v_add_f32_dpp v200, v200, v200 row_half_mirror row_mask:0xf bank_mask:0xf bound_ctrl:1
	ds_read_b128 v[134:137], v42 offset:6912
	v_add_f32_dpp v198, v198, v198 row_mirror row_mask:0xf bank_mask:0xf bound_ctrl:1
	ds_read_b128 v[130:133], v42 offset:6656
	v_add_f32_dpp v200, v200, v200 row_mirror row_mask:0xf bank_mask:0xf bound_ctrl:1
	ds_read_b32 v142, v43 offset:6144
	ds_read_b32 v143, v43 offset:6160
	v_pk_fma_f32 v[2:3], v[126:127], v[198:199], v[2:3] op_sel_hi:[1,0,1] neg_lo:[0,1,0] neg_hi:[0,1,0]
	v_pk_fma_f32 v[4:5], v[128:129], v[198:199], v[4:5] op_sel_hi:[1,0,1] neg_lo:[0,1,0] neg_hi:[0,1,0]
	v_pk_fma_f32 v[6:7], v[126:127], v[200:201], v[6:7] op_sel_hi:[1,0,1] neg_lo:[0,1,0] neg_hi:[0,1,0]
	v_pk_fma_f32 v[8:9], v[128:129], v[200:201], v[8:9] op_sel_hi:[1,0,1] neg_lo:[0,1,0] neg_hi:[0,1,0]
	ds_read_b128 v[122:125], v42 offset:6144
	v_pk_mul_f32 v[194:195], v[140:141], v[4:5]
	v_pk_mul_f32 v[196:197], v[140:141], v[8:9]
	ds_read_b128 v[126:129], v42 offset:6400
	v_pk_fma_f32 v[194:195], v[138:139], v[2:3], v[194:195]
	v_pk_fma_f32 v[196:197], v[138:139], v[6:7], v[196:197]
	ds_read_b128 v[138:141], v42 offset:7168
	v_add_f32_e32 v12, v194, v195
	v_add_f32_e32 v28, v196, v197
	s_waitcnt lgkmcnt(7)
	v_pk_mul_f32 v[176:177], v[2:3], v[166:167]
	v_pk_mul_f32 v[178:179], v[6:7], v[166:167]
	v_pk_fma_f32 v[176:177], v[4:5], v[168:169], v[176:177]
	v_pk_fma_f32 v[178:179], v[8:9], v[168:169], v[178:179]
	v_pk_mul_f32 v[180:181], v[162:163], v[174:175] op_sel_hi:[1,0]
	v_add_f32_e32 v198, v176, v177
	v_pk_mul_f32 v[190:191], v[162:163], v[174:175] op_sel:[0,1] op_sel_hi:[1,1]
	v_add_f32_e32 v200, v178, v179
	v_pk_mul_f32 v[188:189], v[164:165], v[174:175] op_sel_hi:[1,0]
	v_add_f32_dpp v198, v198, v198 quad_perm:[1,0,3,2] row_mask:0xf bank_mask:0xf bound_ctrl:1
	v_pk_mul_f32 v[192:193], v[164:165], v[174:175] op_sel:[0,1] op_sel_hi:[1,1]
	v_add_f32_dpp v200, v200, v200 quad_perm:[1,0,3,2] row_mask:0xf bank_mask:0xf bound_ctrl:1
	v_pk_fma_f32 v[2:3], v[2:3], v[154:155], v[180:181]
	v_add_f32_dpp v198, v198, v198 quad_perm:[2,3,0,1] row_mask:0xf bank_mask:0xf bound_ctrl:1
	v_pk_fma_f32 v[6:7], v[6:7], v[154:155], v[190:191]
	v_add_f32_dpp v200, v200, v200 quad_perm:[2,3,0,1] row_mask:0xf bank_mask:0xf bound_ctrl:1
	v_pk_fma_f32 v[4:5], v[4:5], v[156:157], v[188:189]
	v_add_f32_dpp v198, v198, v198 row_half_mirror row_mask:0xf bank_mask:0xf bound_ctrl:1
	v_pk_fma_f32 v[8:9], v[8:9], v[156:157], v[192:193]
	v_add_f32_dpp v200, v200, v200 row_half_mirror row_mask:0xf bank_mask:0xf bound_ctrl:1
	ds_read_b128 v[166:169], v42 offset:8448
	v_add_f32_dpp v198, v198, v198 row_mirror row_mask:0xf bank_mask:0xf bound_ctrl:1
	ds_read_b128 v[162:165], v42 offset:8192
	v_add_f32_dpp v200, v200, v200 row_mirror row_mask:0xf bank_mask:0xf bound_ctrl:1
	ds_read_b32 v174, v43 offset:7680
	ds_read_b32 v175, v43 offset:7696
	v_pk_fma_f32 v[2:3], v[158:159], v[198:199], v[2:3] op_sel_hi:[1,0,1] neg_lo:[0,1,0] neg_hi:[0,1,0]
	v_pk_fma_f32 v[4:5], v[160:161], v[198:199], v[4:5] op_sel_hi:[1,0,1] neg_lo:[0,1,0] neg_hi:[0,1,0]
	v_pk_fma_f32 v[6:7], v[158:159], v[200:201], v[6:7] op_sel_hi:[1,0,1] neg_lo:[0,1,0] neg_hi:[0,1,0]
	v_pk_fma_f32 v[8:9], v[160:161], v[200:201], v[8:9] op_sel_hi:[1,0,1] neg_lo:[0,1,0] neg_hi:[0,1,0]
	ds_read_b128 v[154:157], v42 offset:7680
	v_pk_mul_f32 v[194:195], v[172:173], v[4:5]
	v_pk_mul_f32 v[196:197], v[172:173], v[8:9]
	ds_read_b128 v[158:161], v42 offset:7936
	v_pk_fma_f32 v[194:195], v[170:171], v[2:3], v[194:195]
	v_pk_fma_f32 v[196:197], v[170:171], v[6:7], v[196:197]
	ds_read_b128 v[170:173], v42 offset:8704
	v_add_f32_e32 v13, v194, v195
	v_add_f32_e32 v29, v196, v197
	s_waitcnt lgkmcnt(7)
	v_pk_mul_f32 v[176:177], v[2:3], v[134:135]
	v_pk_mul_f32 v[178:179], v[6:7], v[134:135]
	v_pk_fma_f32 v[176:177], v[4:5], v[136:137], v[176:177]
	v_pk_fma_f32 v[178:179], v[8:9], v[136:137], v[178:179]
	v_pk_mul_f32 v[180:181], v[130:131], v[142:143] op_sel_hi:[1,0]
	v_add_f32_e32 v198, v176, v177
	v_pk_mul_f32 v[190:191], v[130:131], v[142:143] op_sel:[0,1] op_sel_hi:[1,1]
	v_add_f32_e32 v200, v178, v179
	v_pk_mul_f32 v[188:189], v[132:133], v[142:143] op_sel_hi:[1,0]
	v_add_f32_dpp v198, v198, v198 quad_perm:[1,0,3,2] row_mask:0xf bank_mask:0xf bound_ctrl:1
	v_pk_mul_f32 v[192:193], v[132:133], v[142:143] op_sel:[0,1] op_sel_hi:[1,1]
	v_add_f32_dpp v200, v200, v200 quad_perm:[1,0,3,2] row_mask:0xf bank_mask:0xf bound_ctrl:1
	v_pk_fma_f32 v[2:3], v[2:3], v[122:123], v[180:181]
	v_add_f32_dpp v198, v198, v198 quad_perm:[2,3,0,1] row_mask:0xf bank_mask:0xf bound_ctrl:1
	v_pk_fma_f32 v[6:7], v[6:7], v[122:123], v[190:191]
	v_add_f32_dpp v200, v200, v200 quad_perm:[2,3,0,1] row_mask:0xf bank_mask:0xf bound_ctrl:1
	v_pk_fma_f32 v[4:5], v[4:5], v[124:125], v[188:189]
	v_add_f32_dpp v198, v198, v198 row_half_mirror row_mask:0xf bank_mask:0xf bound_ctrl:1
	v_pk_fma_f32 v[8:9], v[8:9], v[124:125], v[192:193]
	v_add_f32_dpp v200, v200, v200 row_half_mirror row_mask:0xf bank_mask:0xf bound_ctrl:1
	ds_read_b128 v[134:137], v42 offset:9984
	v_add_f32_dpp v198, v198, v198 row_mirror row_mask:0xf bank_mask:0xf bound_ctrl:1
	ds_read_b128 v[130:133], v42 offset:9728
	v_add_f32_dpp v200, v200, v200 row_mirror row_mask:0xf bank_mask:0xf bound_ctrl:1
	ds_read_b32 v142, v43 offset:9216
	ds_read_b32 v143, v43 offset:9232
	v_pk_fma_f32 v[2:3], v[126:127], v[198:199], v[2:3] op_sel_hi:[1,0,1] neg_lo:[0,1,0] neg_hi:[0,1,0]
	v_pk_fma_f32 v[4:5], v[128:129], v[198:199], v[4:5] op_sel_hi:[1,0,1] neg_lo:[0,1,0] neg_hi:[0,1,0]
	v_pk_fma_f32 v[6:7], v[126:127], v[200:201], v[6:7] op_sel_hi:[1,0,1] neg_lo:[0,1,0] neg_hi:[0,1,0]
	v_pk_fma_f32 v[8:9], v[128:129], v[200:201], v[8:9] op_sel_hi:[1,0,1] neg_lo:[0,1,0] neg_hi:[0,1,0]
	ds_read_b128 v[122:125], v42 offset:9216
	v_pk_mul_f32 v[194:195], v[140:141], v[4:5]
	v_pk_mul_f32 v[196:197], v[140:141], v[8:9]
	ds_read_b128 v[126:129], v42 offset:9472
	v_pk_fma_f32 v[194:195], v[138:139], v[2:3], v[194:195]
	v_pk_fma_f32 v[196:197], v[138:139], v[6:7], v[196:197]
	ds_read_b128 v[138:141], v42 offset:10240
	v_add_f32_e32 v14, v194, v195
	v_add_f32_e32 v30, v196, v197
	s_waitcnt lgkmcnt(7)
	v_pk_mul_f32 v[176:177], v[2:3], v[166:167]
	v_pk_mul_f32 v[178:179], v[6:7], v[166:167]
	v_pk_fma_f32 v[176:177], v[4:5], v[168:169], v[176:177]
	v_pk_fma_f32 v[178:179], v[8:9], v[168:169], v[178:179]
	v_pk_mul_f32 v[180:181], v[162:163], v[174:175] op_sel_hi:[1,0]
	v_add_f32_e32 v198, v176, v177
	v_pk_mul_f32 v[190:191], v[162:163], v[174:175] op_sel:[0,1] op_sel_hi:[1,1]
	v_add_f32_e32 v200, v178, v179
	v_pk_mul_f32 v[188:189], v[164:165], v[174:175] op_sel_hi:[1,0]
	v_add_f32_dpp v198, v198, v198 quad_perm:[1,0,3,2] row_mask:0xf bank_mask:0xf bound_ctrl:1
	v_pk_mul_f32 v[192:193], v[164:165], v[174:175] op_sel:[0,1] op_sel_hi:[1,1]
	v_add_f32_dpp v200, v200, v200 quad_perm:[1,0,3,2] row_mask:0xf bank_mask:0xf bound_ctrl:1
	v_pk_fma_f32 v[2:3], v[2:3], v[154:155], v[180:181]
	v_add_f32_dpp v198, v198, v198 quad_perm:[2,3,0,1] row_mask:0xf bank_mask:0xf bound_ctrl:1
	v_pk_fma_f32 v[6:7], v[6:7], v[154:155], v[190:191]
	v_add_f32_dpp v200, v200, v200 quad_perm:[2,3,0,1] row_mask:0xf bank_mask:0xf bound_ctrl:1
	v_pk_fma_f32 v[4:5], v[4:5], v[156:157], v[188:189]
	v_add_f32_dpp v198, v198, v198 row_half_mirror row_mask:0xf bank_mask:0xf bound_ctrl:1
	v_pk_fma_f32 v[8:9], v[8:9], v[156:157], v[192:193]
	v_add_f32_dpp v200, v200, v200 row_half_mirror row_mask:0xf bank_mask:0xf bound_ctrl:1
	ds_read_b128 v[166:169], v42 offset:11520
	v_add_f32_dpp v198, v198, v198 row_mirror row_mask:0xf bank_mask:0xf bound_ctrl:1
	ds_read_b128 v[162:165], v42 offset:11264
	v_add_f32_dpp v200, v200, v200 row_mirror row_mask:0xf bank_mask:0xf bound_ctrl:1
	ds_read_b32 v174, v43 offset:10752
	ds_read_b32 v175, v43 offset:10768
	v_pk_fma_f32 v[2:3], v[158:159], v[198:199], v[2:3] op_sel_hi:[1,0,1] neg_lo:[0,1,0] neg_hi:[0,1,0]
	v_pk_fma_f32 v[4:5], v[160:161], v[198:199], v[4:5] op_sel_hi:[1,0,1] neg_lo:[0,1,0] neg_hi:[0,1,0]
	v_pk_fma_f32 v[6:7], v[158:159], v[200:201], v[6:7] op_sel_hi:[1,0,1] neg_lo:[0,1,0] neg_hi:[0,1,0]
	v_pk_fma_f32 v[8:9], v[160:161], v[200:201], v[8:9] op_sel_hi:[1,0,1] neg_lo:[0,1,0] neg_hi:[0,1,0]
	ds_read_b128 v[154:157], v42 offset:10752
	v_pk_mul_f32 v[194:195], v[172:173], v[4:5]
	v_pk_mul_f32 v[196:197], v[172:173], v[8:9]
	ds_read_b128 v[158:161], v42 offset:11008
	v_pk_fma_f32 v[194:195], v[170:171], v[2:3], v[194:195]
	v_pk_fma_f32 v[196:197], v[170:171], v[6:7], v[196:197]
	ds_read_b128 v[170:173], v42 offset:11776
	v_add_f32_e32 v15, v194, v195
	v_add_f32_e32 v31, v196, v197
	s_waitcnt lgkmcnt(7)
	v_pk_mul_f32 v[176:177], v[2:3], v[134:135]
	v_pk_mul_f32 v[178:179], v[6:7], v[134:135]
	v_pk_fma_f32 v[176:177], v[4:5], v[136:137], v[176:177]
	v_pk_fma_f32 v[178:179], v[8:9], v[136:137], v[178:179]
	v_pk_mul_f32 v[180:181], v[130:131], v[142:143] op_sel_hi:[1,0]
	v_add_f32_e32 v198, v176, v177
	v_pk_mul_f32 v[190:191], v[130:131], v[142:143] op_sel:[0,1] op_sel_hi:[1,1]
	v_add_f32_e32 v200, v178, v179
	v_pk_mul_f32 v[188:189], v[132:133], v[142:143] op_sel_hi:[1,0]
	v_add_f32_dpp v198, v198, v198 quad_perm:[1,0,3,2] row_mask:0xf bank_mask:0xf bound_ctrl:1
	v_pk_mul_f32 v[192:193], v[132:133], v[142:143] op_sel:[0,1] op_sel_hi:[1,1]
	v_add_f32_dpp v200, v200, v200 quad_perm:[1,0,3,2] row_mask:0xf bank_mask:0xf bound_ctrl:1
	v_pk_fma_f32 v[2:3], v[2:3], v[122:123], v[180:181]
	v_add_f32_dpp v198, v198, v198 quad_perm:[2,3,0,1] row_mask:0xf bank_mask:0xf bound_ctrl:1
	v_pk_fma_f32 v[6:7], v[6:7], v[122:123], v[190:191]
	v_add_f32_dpp v200, v200, v200 quad_perm:[2,3,0,1] row_mask:0xf bank_mask:0xf bound_ctrl:1
	v_pk_fma_f32 v[4:5], v[4:5], v[124:125], v[188:189]
	v_add_f32_dpp v198, v198, v198 row_half_mirror row_mask:0xf bank_mask:0xf bound_ctrl:1
	v_pk_fma_f32 v[8:9], v[8:9], v[124:125], v[192:193]
	v_add_f32_dpp v200, v200, v200 row_half_mirror row_mask:0xf bank_mask:0xf bound_ctrl:1
	ds_read_b128 v[134:137], v42 offset:13056
	v_add_f32_dpp v198, v198, v198 row_mirror row_mask:0xf bank_mask:0xf bound_ctrl:1
	ds_read_b128 v[130:133], v42 offset:12800
	v_add_f32_dpp v200, v200, v200 row_mirror row_mask:0xf bank_mask:0xf bound_ctrl:1
	ds_read_b32 v142, v43 offset:12288
	ds_read_b32 v143, v43 offset:12304
	v_pk_fma_f32 v[2:3], v[126:127], v[198:199], v[2:3] op_sel_hi:[1,0,1] neg_lo:[0,1,0] neg_hi:[0,1,0]
	v_pk_fma_f32 v[4:5], v[128:129], v[198:199], v[4:5] op_sel_hi:[1,0,1] neg_lo:[0,1,0] neg_hi:[0,1,0]
	v_pk_fma_f32 v[6:7], v[126:127], v[200:201], v[6:7] op_sel_hi:[1,0,1] neg_lo:[0,1,0] neg_hi:[0,1,0]
	v_pk_fma_f32 v[8:9], v[128:129], v[200:201], v[8:9] op_sel_hi:[1,0,1] neg_lo:[0,1,0] neg_hi:[0,1,0]
	ds_read_b128 v[122:125], v42 offset:12288
	v_pk_mul_f32 v[194:195], v[140:141], v[4:5]
	v_pk_mul_f32 v[196:197], v[140:141], v[8:9]
	ds_read_b128 v[126:129], v42 offset:12544
	v_pk_fma_f32 v[194:195], v[138:139], v[2:3], v[194:195]
	v_pk_fma_f32 v[196:197], v[138:139], v[6:7], v[196:197]
	ds_read_b128 v[138:141], v42 offset:13312
	v_add_f32_e32 v16, v194, v195
	v_add_f32_e32 v32, v196, v197
	s_waitcnt lgkmcnt(7)
	v_pk_mul_f32 v[176:177], v[2:3], v[166:167]
	v_pk_mul_f32 v[178:179], v[6:7], v[166:167]
	v_pk_fma_f32 v[176:177], v[4:5], v[168:169], v[176:177]
	v_pk_fma_f32 v[178:179], v[8:9], v[168:169], v[178:179]
	v_pk_mul_f32 v[180:181], v[162:163], v[174:175] op_sel_hi:[1,0]
	v_add_f32_e32 v198, v176, v177
	v_pk_mul_f32 v[190:191], v[162:163], v[174:175] op_sel:[0,1] op_sel_hi:[1,1]
	v_add_f32_e32 v200, v178, v179
	v_pk_mul_f32 v[188:189], v[164:165], v[174:175] op_sel_hi:[1,0]
	v_add_f32_dpp v198, v198, v198 quad_perm:[1,0,3,2] row_mask:0xf bank_mask:0xf bound_ctrl:1
	v_pk_mul_f32 v[192:193], v[164:165], v[174:175] op_sel:[0,1] op_sel_hi:[1,1]
	v_add_f32_dpp v200, v200, v200 quad_perm:[1,0,3,2] row_mask:0xf bank_mask:0xf bound_ctrl:1
	v_pk_fma_f32 v[2:3], v[2:3], v[154:155], v[180:181]
	v_add_f32_dpp v198, v198, v198 quad_perm:[2,3,0,1] row_mask:0xf bank_mask:0xf bound_ctrl:1
	v_pk_fma_f32 v[6:7], v[6:7], v[154:155], v[190:191]
	v_add_f32_dpp v200, v200, v200 quad_perm:[2,3,0,1] row_mask:0xf bank_mask:0xf bound_ctrl:1
	v_pk_fma_f32 v[4:5], v[4:5], v[156:157], v[188:189]
	v_add_f32_dpp v198, v198, v198 row_half_mirror row_mask:0xf bank_mask:0xf bound_ctrl:1
	v_pk_fma_f32 v[8:9], v[8:9], v[156:157], v[192:193]
	v_add_f32_dpp v200, v200, v200 row_half_mirror row_mask:0xf bank_mask:0xf bound_ctrl:1
	ds_read_b128 v[166:169], v42 offset:14592
	v_add_f32_dpp v198, v198, v198 row_mirror row_mask:0xf bank_mask:0xf bound_ctrl:1
	ds_read_b128 v[162:165], v42 offset:14336
	v_add_f32_dpp v200, v200, v200 row_mirror row_mask:0xf bank_mask:0xf bound_ctrl:1
	ds_read_b32 v174, v43 offset:13824
	ds_read_b32 v175, v43 offset:13840
	v_pk_fma_f32 v[2:3], v[158:159], v[198:199], v[2:3] op_sel_hi:[1,0,1] neg_lo:[0,1,0] neg_hi:[0,1,0]
	v_pk_fma_f32 v[4:5], v[160:161], v[198:199], v[4:5] op_sel_hi:[1,0,1] neg_lo:[0,1,0] neg_hi:[0,1,0]
	v_pk_fma_f32 v[6:7], v[158:159], v[200:201], v[6:7] op_sel_hi:[1,0,1] neg_lo:[0,1,0] neg_hi:[0,1,0]
	v_pk_fma_f32 v[8:9], v[160:161], v[200:201], v[8:9] op_sel_hi:[1,0,1] neg_lo:[0,1,0] neg_hi:[0,1,0]
	ds_read_b128 v[154:157], v42 offset:13824
	v_pk_mul_f32 v[194:195], v[172:173], v[4:5]
	v_pk_mul_f32 v[196:197], v[172:173], v[8:9]
	ds_read_b128 v[158:161], v42 offset:14080
	v_pk_fma_f32 v[194:195], v[170:171], v[2:3], v[194:195]
	v_pk_fma_f32 v[196:197], v[170:171], v[6:7], v[196:197]
	ds_read_b128 v[170:173], v42 offset:14848
	v_add_f32_e32 v17, v194, v195
	v_add_f32_e32 v33, v196, v197
	s_waitcnt lgkmcnt(7)
	v_pk_mul_f32 v[176:177], v[2:3], v[134:135]
	v_pk_mul_f32 v[178:179], v[6:7], v[134:135]
	v_pk_fma_f32 v[176:177], v[4:5], v[136:137], v[176:177]
	v_pk_fma_f32 v[178:179], v[8:9], v[136:137], v[178:179]
	v_pk_mul_f32 v[180:181], v[130:131], v[142:143] op_sel_hi:[1,0]
	v_add_f32_e32 v198, v176, v177
	v_pk_mul_f32 v[190:191], v[130:131], v[142:143] op_sel:[0,1] op_sel_hi:[1,1]
	v_add_f32_e32 v200, v178, v179
	v_pk_mul_f32 v[188:189], v[132:133], v[142:143] op_sel_hi:[1,0]
	v_add_f32_dpp v198, v198, v198 quad_perm:[1,0,3,2] row_mask:0xf bank_mask:0xf bound_ctrl:1
	v_pk_mul_f32 v[192:193], v[132:133], v[142:143] op_sel:[0,1] op_sel_hi:[1,1]
	v_add_f32_dpp v200, v200, v200 quad_perm:[1,0,3,2] row_mask:0xf bank_mask:0xf bound_ctrl:1
	v_pk_fma_f32 v[2:3], v[2:3], v[122:123], v[180:181]
	v_add_f32_dpp v198, v198, v198 quad_perm:[2,3,0,1] row_mask:0xf bank_mask:0xf bound_ctrl:1
	v_pk_fma_f32 v[6:7], v[6:7], v[122:123], v[190:191]
	v_add_f32_dpp v200, v200, v200 quad_perm:[2,3,0,1] row_mask:0xf bank_mask:0xf bound_ctrl:1
	v_pk_fma_f32 v[4:5], v[4:5], v[124:125], v[188:189]
	v_add_f32_dpp v198, v198, v198 row_half_mirror row_mask:0xf bank_mask:0xf bound_ctrl:1
	v_pk_fma_f32 v[8:9], v[8:9], v[124:125], v[192:193]
	v_add_f32_dpp v200, v200, v200 row_half_mirror row_mask:0xf bank_mask:0xf bound_ctrl:1
	ds_read_b128 v[134:137], v42 offset:16128
	v_add_f32_dpp v198, v198, v198 row_mirror row_mask:0xf bank_mask:0xf bound_ctrl:1
	ds_read_b128 v[130:133], v42 offset:15872
	v_add_f32_dpp v200, v200, v200 row_mirror row_mask:0xf bank_mask:0xf bound_ctrl:1
	ds_read_b32 v142, v43 offset:15360
	ds_read_b32 v143, v43 offset:15376
	v_pk_fma_f32 v[2:3], v[126:127], v[198:199], v[2:3] op_sel_hi:[1,0,1] neg_lo:[0,1,0] neg_hi:[0,1,0]
	v_pk_fma_f32 v[4:5], v[128:129], v[198:199], v[4:5] op_sel_hi:[1,0,1] neg_lo:[0,1,0] neg_hi:[0,1,0]
	v_pk_fma_f32 v[6:7], v[126:127], v[200:201], v[6:7] op_sel_hi:[1,0,1] neg_lo:[0,1,0] neg_hi:[0,1,0]
	v_pk_fma_f32 v[8:9], v[128:129], v[200:201], v[8:9] op_sel_hi:[1,0,1] neg_lo:[0,1,0] neg_hi:[0,1,0]
	ds_read_b128 v[122:125], v42 offset:15360
	v_pk_mul_f32 v[194:195], v[140:141], v[4:5]
	v_pk_mul_f32 v[196:197], v[140:141], v[8:9]
	ds_read_b128 v[126:129], v42 offset:15616
	v_pk_fma_f32 v[194:195], v[138:139], v[2:3], v[194:195]
	v_pk_fma_f32 v[196:197], v[138:139], v[6:7], v[196:197]
	ds_read_b128 v[138:141], v42 offset:16384
	v_add_f32_e32 v18, v194, v195
	v_add_f32_e32 v34, v196, v197
	s_waitcnt lgkmcnt(7)
	v_pk_mul_f32 v[176:177], v[2:3], v[166:167]
	v_pk_mul_f32 v[178:179], v[6:7], v[166:167]
	v_pk_fma_f32 v[176:177], v[4:5], v[168:169], v[176:177]
	v_pk_fma_f32 v[178:179], v[8:9], v[168:169], v[178:179]
	v_pk_mul_f32 v[180:181], v[162:163], v[174:175] op_sel_hi:[1,0]
	v_add_f32_e32 v198, v176, v177
	v_pk_mul_f32 v[190:191], v[162:163], v[174:175] op_sel:[0,1] op_sel_hi:[1,1]
	v_add_f32_e32 v200, v178, v179
	v_pk_mul_f32 v[188:189], v[164:165], v[174:175] op_sel_hi:[1,0]
	v_add_f32_dpp v198, v198, v198 quad_perm:[1,0,3,2] row_mask:0xf bank_mask:0xf bound_ctrl:1
	v_pk_mul_f32 v[192:193], v[164:165], v[174:175] op_sel:[0,1] op_sel_hi:[1,1]
	v_add_f32_dpp v200, v200, v200 quad_perm:[1,0,3,2] row_mask:0xf bank_mask:0xf bound_ctrl:1
	v_pk_fma_f32 v[2:3], v[2:3], v[154:155], v[180:181]
	v_add_f32_dpp v198, v198, v198 quad_perm:[2,3,0,1] row_mask:0xf bank_mask:0xf bound_ctrl:1
	v_pk_fma_f32 v[6:7], v[6:7], v[154:155], v[190:191]
	v_add_f32_dpp v200, v200, v200 quad_perm:[2,3,0,1] row_mask:0xf bank_mask:0xf bound_ctrl:1
	v_pk_fma_f32 v[4:5], v[4:5], v[156:157], v[188:189]
	v_add_f32_dpp v198, v198, v198 row_half_mirror row_mask:0xf bank_mask:0xf bound_ctrl:1
	v_pk_fma_f32 v[8:9], v[8:9], v[156:157], v[192:193]
	v_add_f32_dpp v200, v200, v200 row_half_mirror row_mask:0xf bank_mask:0xf bound_ctrl:1
	ds_read_b128 v[166:169], v42 offset:17664
	v_add_f32_dpp v198, v198, v198 row_mirror row_mask:0xf bank_mask:0xf bound_ctrl:1
	ds_read_b128 v[162:165], v42 offset:17408
	v_add_f32_dpp v200, v200, v200 row_mirror row_mask:0xf bank_mask:0xf bound_ctrl:1
	ds_read_b32 v174, v43 offset:16896
	ds_read_b32 v175, v43 offset:16912
	v_pk_fma_f32 v[2:3], v[158:159], v[198:199], v[2:3] op_sel_hi:[1,0,1] neg_lo:[0,1,0] neg_hi:[0,1,0]
	v_pk_fma_f32 v[4:5], v[160:161], v[198:199], v[4:5] op_sel_hi:[1,0,1] neg_lo:[0,1,0] neg_hi:[0,1,0]
	v_pk_fma_f32 v[6:7], v[158:159], v[200:201], v[6:7] op_sel_hi:[1,0,1] neg_lo:[0,1,0] neg_hi:[0,1,0]
	v_pk_fma_f32 v[8:9], v[160:161], v[200:201], v[8:9] op_sel_hi:[1,0,1] neg_lo:[0,1,0] neg_hi:[0,1,0]
	ds_read_b128 v[154:157], v42 offset:16896
	v_pk_mul_f32 v[194:195], v[172:173], v[4:5]
	v_pk_mul_f32 v[196:197], v[172:173], v[8:9]
	ds_read_b128 v[158:161], v42 offset:17152
	v_pk_fma_f32 v[194:195], v[170:171], v[2:3], v[194:195]
	v_pk_fma_f32 v[196:197], v[170:171], v[6:7], v[196:197]
	ds_read_b128 v[170:173], v42 offset:17920
	v_add_f32_e32 v19, v194, v195
	v_add_f32_e32 v35, v196, v197
	s_waitcnt lgkmcnt(7)
	v_pk_mul_f32 v[176:177], v[2:3], v[134:135]
	v_pk_mul_f32 v[178:179], v[6:7], v[134:135]
	v_pk_fma_f32 v[176:177], v[4:5], v[136:137], v[176:177]
	v_pk_fma_f32 v[178:179], v[8:9], v[136:137], v[178:179]
	v_pk_mul_f32 v[180:181], v[130:131], v[142:143] op_sel_hi:[1,0]
	v_add_f32_e32 v198, v176, v177
	v_pk_mul_f32 v[190:191], v[130:131], v[142:143] op_sel:[0,1] op_sel_hi:[1,1]
	v_add_f32_e32 v200, v178, v179
	v_pk_mul_f32 v[188:189], v[132:133], v[142:143] op_sel_hi:[1,0]
	v_add_f32_dpp v198, v198, v198 quad_perm:[1,0,3,2] row_mask:0xf bank_mask:0xf bound_ctrl:1
	v_pk_mul_f32 v[192:193], v[132:133], v[142:143] op_sel:[0,1] op_sel_hi:[1,1]
	v_add_f32_dpp v200, v200, v200 quad_perm:[1,0,3,2] row_mask:0xf bank_mask:0xf bound_ctrl:1
	v_pk_fma_f32 v[2:3], v[2:3], v[122:123], v[180:181]
	v_add_f32_dpp v198, v198, v198 quad_perm:[2,3,0,1] row_mask:0xf bank_mask:0xf bound_ctrl:1
	v_pk_fma_f32 v[6:7], v[6:7], v[122:123], v[190:191]
	v_add_f32_dpp v200, v200, v200 quad_perm:[2,3,0,1] row_mask:0xf bank_mask:0xf bound_ctrl:1
	v_pk_fma_f32 v[4:5], v[4:5], v[124:125], v[188:189]
	v_add_f32_dpp v198, v198, v198 row_half_mirror row_mask:0xf bank_mask:0xf bound_ctrl:1
	v_pk_fma_f32 v[8:9], v[8:9], v[124:125], v[192:193]
	v_add_f32_dpp v200, v200, v200 row_half_mirror row_mask:0xf bank_mask:0xf bound_ctrl:1
	ds_read_b128 v[134:137], v42 offset:19200
	v_add_f32_dpp v198, v198, v198 row_mirror row_mask:0xf bank_mask:0xf bound_ctrl:1
	ds_read_b128 v[130:133], v42 offset:18944
	v_add_f32_dpp v200, v200, v200 row_mirror row_mask:0xf bank_mask:0xf bound_ctrl:1
	ds_read_b32 v142, v43 offset:18432
	ds_read_b32 v143, v43 offset:18448
	v_pk_fma_f32 v[2:3], v[126:127], v[198:199], v[2:3] op_sel_hi:[1,0,1] neg_lo:[0,1,0] neg_hi:[0,1,0]
	v_pk_fma_f32 v[4:5], v[128:129], v[198:199], v[4:5] op_sel_hi:[1,0,1] neg_lo:[0,1,0] neg_hi:[0,1,0]
	v_pk_fma_f32 v[6:7], v[126:127], v[200:201], v[6:7] op_sel_hi:[1,0,1] neg_lo:[0,1,0] neg_hi:[0,1,0]
	v_pk_fma_f32 v[8:9], v[128:129], v[200:201], v[8:9] op_sel_hi:[1,0,1] neg_lo:[0,1,0] neg_hi:[0,1,0]
	ds_read_b128 v[122:125], v42 offset:18432
	v_pk_mul_f32 v[194:195], v[140:141], v[4:5]
	v_pk_mul_f32 v[196:197], v[140:141], v[8:9]
	ds_read_b128 v[126:129], v42 offset:18688
	v_pk_fma_f32 v[194:195], v[138:139], v[2:3], v[194:195]
	v_pk_fma_f32 v[196:197], v[138:139], v[6:7], v[196:197]
	ds_read_b128 v[138:141], v42 offset:19456
	v_add_f32_e32 v20, v194, v195
	v_add_f32_e32 v36, v196, v197
	s_waitcnt lgkmcnt(7)
	v_pk_mul_f32 v[176:177], v[2:3], v[166:167]
	v_pk_mul_f32 v[178:179], v[6:7], v[166:167]
	v_pk_fma_f32 v[176:177], v[4:5], v[168:169], v[176:177]
	v_pk_fma_f32 v[178:179], v[8:9], v[168:169], v[178:179]
	v_pk_mul_f32 v[180:181], v[162:163], v[174:175] op_sel_hi:[1,0]
	v_add_f32_e32 v198, v176, v177
	v_pk_mul_f32 v[190:191], v[162:163], v[174:175] op_sel:[0,1] op_sel_hi:[1,1]
	v_add_f32_e32 v200, v178, v179
	v_pk_mul_f32 v[188:189], v[164:165], v[174:175] op_sel_hi:[1,0]
	v_add_f32_dpp v198, v198, v198 quad_perm:[1,0,3,2] row_mask:0xf bank_mask:0xf bound_ctrl:1
	v_pk_mul_f32 v[192:193], v[164:165], v[174:175] op_sel:[0,1] op_sel_hi:[1,1]
	v_add_f32_dpp v200, v200, v200 quad_perm:[1,0,3,2] row_mask:0xf bank_mask:0xf bound_ctrl:1
	v_pk_fma_f32 v[2:3], v[2:3], v[154:155], v[180:181]
	v_add_f32_dpp v198, v198, v198 quad_perm:[2,3,0,1] row_mask:0xf bank_mask:0xf bound_ctrl:1
	v_pk_fma_f32 v[6:7], v[6:7], v[154:155], v[190:191]
	v_add_f32_dpp v200, v200, v200 quad_perm:[2,3,0,1] row_mask:0xf bank_mask:0xf bound_ctrl:1
	v_pk_fma_f32 v[4:5], v[4:5], v[156:157], v[188:189]
	v_add_f32_dpp v198, v198, v198 row_half_mirror row_mask:0xf bank_mask:0xf bound_ctrl:1
	v_pk_fma_f32 v[8:9], v[8:9], v[156:157], v[192:193]
	v_add_f32_dpp v200, v200, v200 row_half_mirror row_mask:0xf bank_mask:0xf bound_ctrl:1
	ds_read_b128 v[166:169], v42 offset:20736
	v_add_f32_dpp v198, v198, v198 row_mirror row_mask:0xf bank_mask:0xf bound_ctrl:1
	ds_read_b128 v[162:165], v42 offset:20480
	v_add_f32_dpp v200, v200, v200 row_mirror row_mask:0xf bank_mask:0xf bound_ctrl:1
	ds_read_b32 v174, v43 offset:19968
	ds_read_b32 v175, v43 offset:19984
	v_pk_fma_f32 v[2:3], v[158:159], v[198:199], v[2:3] op_sel_hi:[1,0,1] neg_lo:[0,1,0] neg_hi:[0,1,0]
	v_pk_fma_f32 v[4:5], v[160:161], v[198:199], v[4:5] op_sel_hi:[1,0,1] neg_lo:[0,1,0] neg_hi:[0,1,0]
	v_pk_fma_f32 v[6:7], v[158:159], v[200:201], v[6:7] op_sel_hi:[1,0,1] neg_lo:[0,1,0] neg_hi:[0,1,0]
	v_pk_fma_f32 v[8:9], v[160:161], v[200:201], v[8:9] op_sel_hi:[1,0,1] neg_lo:[0,1,0] neg_hi:[0,1,0]
	ds_read_b128 v[154:157], v42 offset:19968
	v_pk_mul_f32 v[194:195], v[172:173], v[4:5]
	v_pk_mul_f32 v[196:197], v[172:173], v[8:9]
	ds_read_b128 v[158:161], v42 offset:20224
	v_pk_fma_f32 v[194:195], v[170:171], v[2:3], v[194:195]
	v_pk_fma_f32 v[196:197], v[170:171], v[6:7], v[196:197]
	ds_read_b128 v[170:173], v42 offset:20992
	v_add_f32_e32 v21, v194, v195
	v_add_f32_e32 v37, v196, v197
	s_waitcnt lgkmcnt(7)
	v_pk_mul_f32 v[176:177], v[2:3], v[134:135]
	v_pk_mul_f32 v[178:179], v[6:7], v[134:135]
	v_pk_fma_f32 v[176:177], v[4:5], v[136:137], v[176:177]
	v_pk_fma_f32 v[178:179], v[8:9], v[136:137], v[178:179]
	v_pk_mul_f32 v[180:181], v[130:131], v[142:143] op_sel_hi:[1,0]
	v_add_f32_e32 v198, v176, v177
	v_pk_mul_f32 v[190:191], v[130:131], v[142:143] op_sel:[0,1] op_sel_hi:[1,1]
	v_add_f32_e32 v200, v178, v179
	v_pk_mul_f32 v[188:189], v[132:133], v[142:143] op_sel_hi:[1,0]
	v_add_f32_dpp v198, v198, v198 quad_perm:[1,0,3,2] row_mask:0xf bank_mask:0xf bound_ctrl:1
	v_pk_mul_f32 v[192:193], v[132:133], v[142:143] op_sel:[0,1] op_sel_hi:[1,1]
	v_add_f32_dpp v200, v200, v200 quad_perm:[1,0,3,2] row_mask:0xf bank_mask:0xf bound_ctrl:1
	v_pk_fma_f32 v[2:3], v[2:3], v[122:123], v[180:181]
	v_add_f32_dpp v198, v198, v198 quad_perm:[2,3,0,1] row_mask:0xf bank_mask:0xf bound_ctrl:1
	v_pk_fma_f32 v[6:7], v[6:7], v[122:123], v[190:191]
	v_add_f32_dpp v200, v200, v200 quad_perm:[2,3,0,1] row_mask:0xf bank_mask:0xf bound_ctrl:1
	v_pk_fma_f32 v[4:5], v[4:5], v[124:125], v[188:189]
	v_add_f32_dpp v198, v198, v198 row_half_mirror row_mask:0xf bank_mask:0xf bound_ctrl:1
	v_pk_fma_f32 v[8:9], v[8:9], v[124:125], v[192:193]
	v_add_f32_dpp v200, v200, v200 row_half_mirror row_mask:0xf bank_mask:0xf bound_ctrl:1
	ds_read_b128 v[134:137], v42 offset:22272
	v_add_f32_dpp v198, v198, v198 row_mirror row_mask:0xf bank_mask:0xf bound_ctrl:1
	ds_read_b128 v[130:133], v42 offset:22016
	v_add_f32_dpp v200, v200, v200 row_mirror row_mask:0xf bank_mask:0xf bound_ctrl:1
	ds_read_b32 v142, v43 offset:21504
	ds_read_b32 v143, v43 offset:21520
	v_pk_fma_f32 v[2:3], v[126:127], v[198:199], v[2:3] op_sel_hi:[1,0,1] neg_lo:[0,1,0] neg_hi:[0,1,0]
	v_pk_fma_f32 v[4:5], v[128:129], v[198:199], v[4:5] op_sel_hi:[1,0,1] neg_lo:[0,1,0] neg_hi:[0,1,0]
	v_pk_fma_f32 v[6:7], v[126:127], v[200:201], v[6:7] op_sel_hi:[1,0,1] neg_lo:[0,1,0] neg_hi:[0,1,0]
	v_pk_fma_f32 v[8:9], v[128:129], v[200:201], v[8:9] op_sel_hi:[1,0,1] neg_lo:[0,1,0] neg_hi:[0,1,0]
	ds_read_b128 v[122:125], v42 offset:21504
	v_pk_mul_f32 v[194:195], v[140:141], v[4:5]
	v_pk_mul_f32 v[196:197], v[140:141], v[8:9]
	ds_read_b128 v[126:129], v42 offset:21760
	v_pk_fma_f32 v[194:195], v[138:139], v[2:3], v[194:195]
	v_pk_fma_f32 v[196:197], v[138:139], v[6:7], v[196:197]
	ds_read_b128 v[138:141], v42 offset:22528
	v_add_f32_e32 v22, v194, v195
	v_add_f32_e32 v38, v196, v197
	s_waitcnt lgkmcnt(7)
	v_pk_mul_f32 v[176:177], v[2:3], v[166:167]
	v_pk_mul_f32 v[178:179], v[6:7], v[166:167]
	v_pk_fma_f32 v[176:177], v[4:5], v[168:169], v[176:177]
	v_pk_fma_f32 v[178:179], v[8:9], v[168:169], v[178:179]
	v_pk_mul_f32 v[180:181], v[162:163], v[174:175] op_sel_hi:[1,0]
	v_add_f32_e32 v198, v176, v177
	v_pk_mul_f32 v[190:191], v[162:163], v[174:175] op_sel:[0,1] op_sel_hi:[1,1]
	v_add_f32_e32 v200, v178, v179
	v_pk_mul_f32 v[188:189], v[164:165], v[174:175] op_sel_hi:[1,0]
	v_add_f32_dpp v198, v198, v198 quad_perm:[1,0,3,2] row_mask:0xf bank_mask:0xf bound_ctrl:1
	v_pk_mul_f32 v[192:193], v[164:165], v[174:175] op_sel:[0,1] op_sel_hi:[1,1]
	v_add_f32_dpp v200, v200, v200 quad_perm:[1,0,3,2] row_mask:0xf bank_mask:0xf bound_ctrl:1
	v_pk_fma_f32 v[2:3], v[2:3], v[154:155], v[180:181]
	v_add_f32_dpp v198, v198, v198 quad_perm:[2,3,0,1] row_mask:0xf bank_mask:0xf bound_ctrl:1
	v_pk_fma_f32 v[6:7], v[6:7], v[154:155], v[190:191]
	v_add_f32_dpp v200, v200, v200 quad_perm:[2,3,0,1] row_mask:0xf bank_mask:0xf bound_ctrl:1
	v_pk_fma_f32 v[4:5], v[4:5], v[156:157], v[188:189]
	v_add_f32_dpp v198, v198, v198 row_half_mirror row_mask:0xf bank_mask:0xf bound_ctrl:1
	v_pk_fma_f32 v[8:9], v[8:9], v[156:157], v[192:193]
	v_add_f32_dpp v200, v200, v200 row_half_mirror row_mask:0xf bank_mask:0xf bound_ctrl:1
	ds_read_b128 v[166:169], v42 offset:23808
	v_add_f32_dpp v198, v198, v198 row_mirror row_mask:0xf bank_mask:0xf bound_ctrl:1
	ds_read_b128 v[162:165], v42 offset:23552
	v_add_f32_dpp v200, v200, v200 row_mirror row_mask:0xf bank_mask:0xf bound_ctrl:1
	ds_read_b32 v174, v43 offset:23040
	ds_read_b32 v175, v43 offset:23056
	v_pk_fma_f32 v[2:3], v[158:159], v[198:199], v[2:3] op_sel_hi:[1,0,1] neg_lo:[0,1,0] neg_hi:[0,1,0]
	v_pk_fma_f32 v[4:5], v[160:161], v[198:199], v[4:5] op_sel_hi:[1,0,1] neg_lo:[0,1,0] neg_hi:[0,1,0]
	v_pk_fma_f32 v[6:7], v[158:159], v[200:201], v[6:7] op_sel_hi:[1,0,1] neg_lo:[0,1,0] neg_hi:[0,1,0]
	v_pk_fma_f32 v[8:9], v[160:161], v[200:201], v[8:9] op_sel_hi:[1,0,1] neg_lo:[0,1,0] neg_hi:[0,1,0]
	ds_read_b128 v[154:157], v42 offset:23040
	v_pk_mul_f32 v[194:195], v[172:173], v[4:5]
	v_pk_mul_f32 v[196:197], v[172:173], v[8:9]
	ds_read_b128 v[158:161], v42 offset:23296
	v_pk_fma_f32 v[194:195], v[170:171], v[2:3], v[194:195]
	v_pk_fma_f32 v[196:197], v[170:171], v[6:7], v[196:197]
	ds_read_b128 v[170:173], v42 offset:24064
	v_add_f32_e32 v23, v194, v195
	v_add_f32_e32 v39, v196, v197
	s_waitcnt lgkmcnt(7)
	v_pk_mul_f32 v[176:177], v[2:3], v[134:135]
	v_pk_mul_f32 v[178:179], v[6:7], v[134:135]
	v_pk_fma_f32 v[176:177], v[4:5], v[136:137], v[176:177]
	v_pk_fma_f32 v[178:179], v[8:9], v[136:137], v[178:179]
	v_pk_mul_f32 v[180:181], v[130:131], v[142:143] op_sel_hi:[1,0]
	v_add_f32_e32 v198, v176, v177
	v_pk_mul_f32 v[190:191], v[130:131], v[142:143] op_sel:[0,1] op_sel_hi:[1,1]
	v_add_f32_e32 v200, v178, v179
	v_pk_mul_f32 v[188:189], v[132:133], v[142:143] op_sel_hi:[1,0]
	v_add_f32_dpp v198, v198, v198 quad_perm:[1,0,3,2] row_mask:0xf bank_mask:0xf bound_ctrl:1
	v_pk_mul_f32 v[192:193], v[132:133], v[142:143] op_sel:[0,1] op_sel_hi:[1,1]
	v_add_f32_dpp v200, v200, v200 quad_perm:[1,0,3,2] row_mask:0xf bank_mask:0xf bound_ctrl:1
	v_pk_fma_f32 v[2:3], v[2:3], v[122:123], v[180:181]
	v_add_f32_dpp v198, v198, v198 quad_perm:[2,3,0,1] row_mask:0xf bank_mask:0xf bound_ctrl:1
	v_pk_fma_f32 v[6:7], v[6:7], v[122:123], v[190:191]
	v_add_f32_dpp v200, v200, v200 quad_perm:[2,3,0,1] row_mask:0xf bank_mask:0xf bound_ctrl:1
	v_pk_fma_f32 v[4:5], v[4:5], v[124:125], v[188:189]
	v_add_f32_dpp v198, v198, v198 row_half_mirror row_mask:0xf bank_mask:0xf bound_ctrl:1
	v_pk_fma_f32 v[8:9], v[8:9], v[124:125], v[192:193]
	v_add_f32_dpp v200, v200, v200 row_half_mirror row_mask:0xf bank_mask:0xf bound_ctrl:1
	ds_read_b128 v[134:137], v42 offset:25344
	v_add_f32_dpp v198, v198, v198 row_mirror row_mask:0xf bank_mask:0xf bound_ctrl:1
	ds_read_b128 v[130:133], v42 offset:25088
	v_add_f32_dpp v200, v200, v200 row_mirror row_mask:0xf bank_mask:0xf bound_ctrl:1
	ds_read_b32 v142, v43 offset:24576
	ds_read_b32 v143, v43 offset:24592
	v_pk_fma_f32 v[2:3], v[126:127], v[198:199], v[2:3] op_sel_hi:[1,0,1] neg_lo:[0,1,0] neg_hi:[0,1,0]
	v_pk_fma_f32 v[4:5], v[128:129], v[198:199], v[4:5] op_sel_hi:[1,0,1] neg_lo:[0,1,0] neg_hi:[0,1,0]
	v_pk_fma_f32 v[6:7], v[126:127], v[200:201], v[6:7] op_sel_hi:[1,0,1] neg_lo:[0,1,0] neg_hi:[0,1,0]
	v_pk_fma_f32 v[8:9], v[128:129], v[200:201], v[8:9] op_sel_hi:[1,0,1] neg_lo:[0,1,0] neg_hi:[0,1,0]
	ds_read_b128 v[122:125], v42 offset:24576
	v_pk_mul_f32 v[194:195], v[140:141], v[4:5]
	v_pk_mul_f32 v[196:197], v[140:141], v[8:9]
	ds_read_b128 v[126:129], v42 offset:24832
	v_pk_fma_f32 v[194:195], v[138:139], v[2:3], v[194:195]
	v_pk_fma_f32 v[196:197], v[138:139], v[6:7], v[196:197]
	ds_read_b128 v[138:141], v42 offset:25600
	v_add_f32_e32 v24, v194, v195
	v_add_f32_e32 v40, v196, v197
	s_waitcnt lgkmcnt(7)
	v_pk_mul_f32 v[176:177], v[2:3], v[166:167]
	v_pk_mul_f32 v[178:179], v[6:7], v[166:167]
	v_pk_fma_f32 v[176:177], v[4:5], v[168:169], v[176:177]
	v_pk_fma_f32 v[178:179], v[8:9], v[168:169], v[178:179]
	v_pk_mul_f32 v[180:181], v[162:163], v[174:175] op_sel_hi:[1,0]
	v_add_f32_e32 v198, v176, v177
	v_pk_mul_f32 v[190:191], v[162:163], v[174:175] op_sel:[0,1] op_sel_hi:[1,1]
	v_add_f32_e32 v200, v178, v179
	v_pk_mul_f32 v[188:189], v[164:165], v[174:175] op_sel_hi:[1,0]
	v_add_f32_dpp v198, v198, v198 quad_perm:[1,0,3,2] row_mask:0xf bank_mask:0xf bound_ctrl:1
	v_pk_mul_f32 v[192:193], v[164:165], v[174:175] op_sel:[0,1] op_sel_hi:[1,1]
	v_add_f32_dpp v200, v200, v200 quad_perm:[1,0,3,2] row_mask:0xf bank_mask:0xf bound_ctrl:1
	v_pk_fma_f32 v[2:3], v[2:3], v[154:155], v[180:181]
	v_add_f32_dpp v198, v198, v198 quad_perm:[2,3,0,1] row_mask:0xf bank_mask:0xf bound_ctrl:1
	v_pk_fma_f32 v[6:7], v[6:7], v[154:155], v[190:191]
	v_add_f32_dpp v200, v200, v200 quad_perm:[2,3,0,1] row_mask:0xf bank_mask:0xf bound_ctrl:1
	v_pk_fma_f32 v[4:5], v[4:5], v[156:157], v[188:189]
	v_add_f32_dpp v198, v198, v198 row_half_mirror row_mask:0xf bank_mask:0xf bound_ctrl:1
	v_pk_fma_f32 v[8:9], v[8:9], v[156:157], v[192:193]
	v_add_f32_dpp v200, v200, v200 row_half_mirror row_mask:0xf bank_mask:0xf bound_ctrl:1
	ds_read_b128 v[166:169], v42 offset:26880
	v_add_f32_dpp v198, v198, v198 row_mirror row_mask:0xf bank_mask:0xf bound_ctrl:1
	ds_read_b128 v[162:165], v42 offset:26624
	v_add_f32_dpp v200, v200, v200 row_mirror row_mask:0xf bank_mask:0xf bound_ctrl:1
	ds_read_b32 v174, v43 offset:26112
	ds_read_b32 v175, v43 offset:26128
	v_pk_fma_f32 v[2:3], v[158:159], v[198:199], v[2:3] op_sel_hi:[1,0,1] neg_lo:[0,1,0] neg_hi:[0,1,0]
	v_pk_fma_f32 v[4:5], v[160:161], v[198:199], v[4:5] op_sel_hi:[1,0,1] neg_lo:[0,1,0] neg_hi:[0,1,0]
	v_pk_fma_f32 v[6:7], v[158:159], v[200:201], v[6:7] op_sel_hi:[1,0,1] neg_lo:[0,1,0] neg_hi:[0,1,0]
	v_pk_fma_f32 v[8:9], v[160:161], v[200:201], v[8:9] op_sel_hi:[1,0,1] neg_lo:[0,1,0] neg_hi:[0,1,0]
	ds_read_b128 v[154:157], v42 offset:26112
	v_pk_mul_f32 v[194:195], v[172:173], v[4:5]
	v_pk_mul_f32 v[196:197], v[172:173], v[8:9]
	ds_read_b128 v[158:161], v42 offset:26368
	v_pk_fma_f32 v[194:195], v[170:171], v[2:3], v[194:195]
	v_pk_fma_f32 v[196:197], v[170:171], v[6:7], v[196:197]
	ds_read_b128 v[170:173], v42 offset:27136
	v_add_f32_e32 v25, v194, v195
	v_add_f32_e32 v41, v196, v197
	v_cndmask_b32_e64 v176, v10, v18, s[56:57]
	v_cndmask_b32_e64 v177, v18, v10, s[56:57]
	v_cndmask_b32_e64 v178, v11, v19, s[56:57]
	v_cndmask_b32_e64 v179, v19, v11, s[56:57]
	v_cndmask_b32_e64 v180, v12, v20, s[56:57]
	v_cndmask_b32_e64 v181, v20, v12, s[56:57]
	v_cndmask_b32_e64 v188, v13, v21, s[56:57]
	v_cndmask_b32_e64 v189, v21, v13, s[56:57]
	v_add_f32_dpp v190, v177, v176 row_mirror row_mask:0xf bank_mask:0xf bound_ctrl:1
	v_add_f32_dpp v191, v179, v178 row_mirror row_mask:0xf bank_mask:0xf bound_ctrl:1
	v_add_f32_dpp v192, v181, v180 row_mirror row_mask:0xf bank_mask:0xf bound_ctrl:1
	v_add_f32_dpp v193, v189, v188 row_mirror row_mask:0xf bank_mask:0xf bound_ctrl:1
	v_cndmask_b32_e64 v176, v14, v22, s[56:57]
	v_cndmask_b32_e64 v177, v22, v14, s[56:57]
	v_cndmask_b32_e64 v178, v15, v23, s[56:57]
	v_cndmask_b32_e64 v179, v23, v15, s[56:57]
	v_cndmask_b32_e64 v180, v16, v24, s[56:57]
	v_cndmask_b32_e64 v181, v24, v16, s[56:57]
	v_cndmask_b32_e64 v188, v17, v25, s[56:57]
	v_cndmask_b32_e64 v189, v25, v17, s[56:57]
	v_add_f32_dpp v194, v177, v176 row_mirror row_mask:0xf bank_mask:0xf bound_ctrl:1
	v_add_f32_dpp v195, v179, v178 row_mirror row_mask:0xf bank_mask:0xf bound_ctrl:1
	v_add_f32_dpp v196, v181, v180 row_mirror row_mask:0xf bank_mask:0xf bound_ctrl:1
	v_add_f32_dpp v197, v189, v188 row_mirror row_mask:0xf bank_mask:0xf bound_ctrl:1
	v_cndmask_b32_e64 v176, v190, v194, s[82:83]
	v_cndmask_b32_e64 v177, v194, v190, s[82:83]
	v_cndmask_b32_e64 v178, v191, v195, s[82:83]
	v_cndmask_b32_e64 v179, v195, v191, s[82:83]
	v_cndmask_b32_e64 v180, v192, v196, s[82:83]
	v_cndmask_b32_e64 v181, v196, v192, s[82:83]
	v_cndmask_b32_e64 v188, v193, v197, s[82:83]
	v_cndmask_b32_e64 v189, v197, v193, s[82:83]
	v_add_f32_dpp v202, v177, v176 row_half_mirror row_mask:0xf bank_mask:0xf bound_ctrl:1
	v_add_f32_dpp v203, v179, v178 row_half_mirror row_mask:0xf bank_mask:0xf bound_ctrl:1
	v_add_f32_dpp v204, v181, v180 row_half_mirror row_mask:0xf bank_mask:0xf bound_ctrl:1
	v_add_f32_dpp v205, v189, v188 row_half_mirror row_mask:0xf bank_mask:0xf bound_ctrl:1
	v_cndmask_b32_e64 v176, v202, v204, s[84:85]
	v_cndmask_b32_e64 v177, v204, v202, s[84:85]
	v_cndmask_b32_e64 v178, v203, v205, s[84:85]
	v_cndmask_b32_e64 v179, v205, v203, s[84:85]
	s_nop 1
	v_add_f32_dpp v210, v177, v176 quad_perm:[2,3,0,1] row_mask:0xf bank_mask:0xf bound_ctrl:1
	v_add_f32_dpp v211, v179, v178 quad_perm:[2,3,0,1] row_mask:0xf bank_mask:0xf bound_ctrl:1
	s_nop 0
	v_cndmask_b32_e64 v176, v210, v211, s[88:89]
	v_cndmask_b32_e64 v177, v211, v210, s[88:89]
	s_nop 1
	v_add_f32_dpp v212, v177, v176 quad_perm:[1,0,3,2] row_mask:0xf bank_mask:0xf bound_ctrl:1
	ds_write_b32 v44, v212 offset:0
	v_cndmask_b32_e64 v176, v26, v34, s[56:57]
	v_cndmask_b32_e64 v177, v34, v26, s[56:57]
	v_cndmask_b32_e64 v178, v27, v35, s[56:57]
	v_cndmask_b32_e64 v179, v35, v27, s[56:57]
	v_cndmask_b32_e64 v180, v28, v36, s[56:57]
	v_cndmask_b32_e64 v181, v36, v28, s[56:57]
	v_cndmask_b32_e64 v188, v29, v37, s[56:57]
	v_cndmask_b32_e64 v189, v37, v29, s[56:57]
	v_add_f32_dpp v190, v177, v176 row_mirror row_mask:0xf bank_mask:0xf bound_ctrl:1
	v_add_f32_dpp v191, v179, v178 row_mirror row_mask:0xf bank_mask:0xf bound_ctrl:1
	v_add_f32_dpp v192, v181, v180 row_mirror row_mask:0xf bank_mask:0xf bound_ctrl:1
	v_add_f32_dpp v193, v189, v188 row_mirror row_mask:0xf bank_mask:0xf bound_ctrl:1
	v_cndmask_b32_e64 v176, v30, v38, s[56:57]
	v_cndmask_b32_e64 v177, v38, v30, s[56:57]
	v_cndmask_b32_e64 v178, v31, v39, s[56:57]
	v_cndmask_b32_e64 v179, v39, v31, s[56:57]
	v_cndmask_b32_e64 v180, v32, v40, s[56:57]
	v_cndmask_b32_e64 v181, v40, v32, s[56:57]
	v_cndmask_b32_e64 v188, v33, v41, s[56:57]
	v_cndmask_b32_e64 v189, v41, v33, s[56:57]
	v_add_f32_dpp v194, v177, v176 row_mirror row_mask:0xf bank_mask:0xf bound_ctrl:1
	v_add_f32_dpp v195, v179, v178 row_mirror row_mask:0xf bank_mask:0xf bound_ctrl:1
	v_add_f32_dpp v196, v181, v180 row_mirror row_mask:0xf bank_mask:0xf bound_ctrl:1
	v_add_f32_dpp v197, v189, v188 row_mirror row_mask:0xf bank_mask:0xf bound_ctrl:1
	v_cndmask_b32_e64 v176, v190, v194, s[82:83]
	v_cndmask_b32_e64 v177, v194, v190, s[82:83]
	v_cndmask_b32_e64 v178, v191, v195, s[82:83]
	v_cndmask_b32_e64 v179, v195, v191, s[82:83]
	v_cndmask_b32_e64 v180, v192, v196, s[82:83]
	v_cndmask_b32_e64 v181, v196, v192, s[82:83]
	v_cndmask_b32_e64 v188, v193, v197, s[82:83]
	v_cndmask_b32_e64 v189, v197, v193, s[82:83]
	v_add_f32_dpp v202, v177, v176 row_half_mirror row_mask:0xf bank_mask:0xf bound_ctrl:1
	v_add_f32_dpp v203, v179, v178 row_half_mirror row_mask:0xf bank_mask:0xf bound_ctrl:1
	v_add_f32_dpp v204, v181, v180 row_half_mirror row_mask:0xf bank_mask:0xf bound_ctrl:1
	v_add_f32_dpp v205, v189, v188 row_half_mirror row_mask:0xf bank_mask:0xf bound_ctrl:1
	v_cndmask_b32_e64 v176, v202, v204, s[84:85]
	v_cndmask_b32_e64 v177, v204, v202, s[84:85]
	v_cndmask_b32_e64 v178, v203, v205, s[84:85]
	v_cndmask_b32_e64 v179, v205, v203, s[84:85]
	s_nop 1
	v_add_f32_dpp v210, v177, v176 quad_perm:[2,3,0,1] row_mask:0xf bank_mask:0xf bound_ctrl:1
	v_add_f32_dpp v211, v179, v178 quad_perm:[2,3,0,1] row_mask:0xf bank_mask:0xf bound_ctrl:1
	s_nop 0
	v_cndmask_b32_e64 v176, v210, v211, s[88:89]
	v_cndmask_b32_e64 v177, v211, v210, s[88:89]
	s_nop 1
	v_add_f32_dpp v212, v177, v176 quad_perm:[1,0,3,2] row_mask:0xf bank_mask:0xf bound_ctrl:1
	ds_write_b32 v44, v212 offset:16
	s_waitcnt lgkmcnt(9)
	v_pk_mul_f32 v[176:177], v[2:3], v[134:135]
	v_pk_mul_f32 v[178:179], v[6:7], v[134:135]
	v_pk_fma_f32 v[176:177], v[4:5], v[136:137], v[176:177]
	v_pk_fma_f32 v[178:179], v[8:9], v[136:137], v[178:179]
	v_pk_mul_f32 v[180:181], v[130:131], v[142:143] op_sel_hi:[1,0]
	v_add_f32_e32 v198, v176, v177
	v_pk_mul_f32 v[190:191], v[130:131], v[142:143] op_sel:[0,1] op_sel_hi:[1,1]
	v_add_f32_e32 v200, v178, v179
	v_pk_mul_f32 v[188:189], v[132:133], v[142:143] op_sel_hi:[1,0]
	v_add_f32_dpp v198, v198, v198 quad_perm:[1,0,3,2] row_mask:0xf bank_mask:0xf bound_ctrl:1
	v_pk_mul_f32 v[192:193], v[132:133], v[142:143] op_sel:[0,1] op_sel_hi:[1,1]
	v_add_f32_dpp v200, v200, v200 quad_perm:[1,0,3,2] row_mask:0xf bank_mask:0xf bound_ctrl:1
	v_pk_fma_f32 v[2:3], v[2:3], v[122:123], v[180:181]
	v_add_f32_dpp v198, v198, v198 quad_perm:[2,3,0,1] row_mask:0xf bank_mask:0xf bound_ctrl:1
	v_pk_fma_f32 v[6:7], v[6:7], v[122:123], v[190:191]
	v_add_f32_dpp v200, v200, v200 quad_perm:[2,3,0,1] row_mask:0xf bank_mask:0xf bound_ctrl:1
	v_pk_fma_f32 v[4:5], v[4:5], v[124:125], v[188:189]
	v_add_f32_dpp v198, v198, v198 row_half_mirror row_mask:0xf bank_mask:0xf bound_ctrl:1
	v_pk_fma_f32 v[8:9], v[8:9], v[124:125], v[192:193]
	v_add_f32_dpp v200, v200, v200 row_half_mirror row_mask:0xf bank_mask:0xf bound_ctrl:1
	ds_read_b128 v[134:137], v42 offset:28416
	v_add_f32_dpp v198, v198, v198 row_mirror row_mask:0xf bank_mask:0xf bound_ctrl:1
	ds_read_b128 v[130:133], v42 offset:28160
	v_add_f32_dpp v200, v200, v200 row_mirror row_mask:0xf bank_mask:0xf bound_ctrl:1
	ds_read_b32 v142, v43 offset:27648
	ds_read_b32 v143, v43 offset:27664
	v_pk_fma_f32 v[2:3], v[126:127], v[198:199], v[2:3] op_sel_hi:[1,0,1] neg_lo:[0,1,0] neg_hi:[0,1,0]
	v_pk_fma_f32 v[4:5], v[128:129], v[198:199], v[4:5] op_sel_hi:[1,0,1] neg_lo:[0,1,0] neg_hi:[0,1,0]
	v_pk_fma_f32 v[6:7], v[126:127], v[200:201], v[6:7] op_sel_hi:[1,0,1] neg_lo:[0,1,0] neg_hi:[0,1,0]
	v_pk_fma_f32 v[8:9], v[128:129], v[200:201], v[8:9] op_sel_hi:[1,0,1] neg_lo:[0,1,0] neg_hi:[0,1,0]
	ds_read_b128 v[122:125], v42 offset:27648
	v_pk_mul_f32 v[194:195], v[140:141], v[4:5]
	v_pk_mul_f32 v[196:197], v[140:141], v[8:9]
	ds_read_b128 v[126:129], v42 offset:27904
	v_pk_fma_f32 v[194:195], v[138:139], v[2:3], v[194:195]
	v_pk_fma_f32 v[196:197], v[138:139], v[6:7], v[196:197]
	ds_read_b128 v[138:141], v42 offset:28672
	v_add_f32_e32 v10, v194, v195
	v_add_f32_e32 v26, v196, v197
	s_waitcnt lgkmcnt(9)
	v_pk_mul_f32 v[176:177], v[2:3], v[166:167]
	v_pk_mul_f32 v[178:179], v[6:7], v[166:167]
	v_pk_fma_f32 v[176:177], v[4:5], v[168:169], v[176:177]
	v_pk_fma_f32 v[178:179], v[8:9], v[168:169], v[178:179]
	v_pk_mul_f32 v[180:181], v[162:163], v[174:175] op_sel_hi:[1,0]
	v_add_f32_e32 v198, v176, v177
	v_pk_mul_f32 v[190:191], v[162:163], v[174:175] op_sel:[0,1] op_sel_hi:[1,1]
	v_add_f32_e32 v200, v178, v179
	v_pk_mul_f32 v[188:189], v[164:165], v[174:175] op_sel_hi:[1,0]
	v_add_f32_dpp v198, v198, v198 quad_perm:[1,0,3,2] row_mask:0xf bank_mask:0xf bound_ctrl:1
	v_pk_mul_f32 v[192:193], v[164:165], v[174:175] op_sel:[0,1] op_sel_hi:[1,1]
	v_add_f32_dpp v200, v200, v200 quad_perm:[1,0,3,2] row_mask:0xf bank_mask:0xf bound_ctrl:1
	v_pk_fma_f32 v[2:3], v[2:3], v[154:155], v[180:181]
	v_add_f32_dpp v198, v198, v198 quad_perm:[2,3,0,1] row_mask:0xf bank_mask:0xf bound_ctrl:1
	v_pk_fma_f32 v[6:7], v[6:7], v[154:155], v[190:191]
	v_add_f32_dpp v200, v200, v200 quad_perm:[2,3,0,1] row_mask:0xf bank_mask:0xf bound_ctrl:1
	v_pk_fma_f32 v[4:5], v[4:5], v[156:157], v[188:189]
	v_add_f32_dpp v198, v198, v198 row_half_mirror row_mask:0xf bank_mask:0xf bound_ctrl:1
	v_pk_fma_f32 v[8:9], v[8:9], v[156:157], v[192:193]
	v_add_f32_dpp v200, v200, v200 row_half_mirror row_mask:0xf bank_mask:0xf bound_ctrl:1
	ds_read_b128 v[166:169], v42 offset:29952
	v_add_f32_dpp v198, v198, v198 row_mirror row_mask:0xf bank_mask:0xf bound_ctrl:1
	ds_read_b128 v[162:165], v42 offset:29696
	v_add_f32_dpp v200, v200, v200 row_mirror row_mask:0xf bank_mask:0xf bound_ctrl:1
	ds_read_b32 v174, v43 offset:29184
	ds_read_b32 v175, v43 offset:29200
	v_pk_fma_f32 v[2:3], v[158:159], v[198:199], v[2:3] op_sel_hi:[1,0,1] neg_lo:[0,1,0] neg_hi:[0,1,0]
	v_pk_fma_f32 v[4:5], v[160:161], v[198:199], v[4:5] op_sel_hi:[1,0,1] neg_lo:[0,1,0] neg_hi:[0,1,0]
	v_pk_fma_f32 v[6:7], v[158:159], v[200:201], v[6:7] op_sel_hi:[1,0,1] neg_lo:[0,1,0] neg_hi:[0,1,0]
	v_pk_fma_f32 v[8:9], v[160:161], v[200:201], v[8:9] op_sel_hi:[1,0,1] neg_lo:[0,1,0] neg_hi:[0,1,0]
	ds_read_b128 v[154:157], v42 offset:29184
	v_pk_mul_f32 v[194:195], v[172:173], v[4:5]
	v_pk_mul_f32 v[196:197], v[172:173], v[8:9]
	ds_read_b128 v[158:161], v42 offset:29440
	v_pk_fma_f32 v[194:195], v[170:171], v[2:3], v[194:195]
	v_pk_fma_f32 v[196:197], v[170:171], v[6:7], v[196:197]
	ds_read_b128 v[170:173], v42 offset:30208
	v_add_f32_e32 v11, v194, v195
	v_add_f32_e32 v27, v196, v197
	s_waitcnt lgkmcnt(7)
	v_pk_mul_f32 v[176:177], v[2:3], v[134:135]
	v_pk_mul_f32 v[178:179], v[6:7], v[134:135]
	v_pk_fma_f32 v[176:177], v[4:5], v[136:137], v[176:177]
	v_pk_fma_f32 v[178:179], v[8:9], v[136:137], v[178:179]
	v_pk_mul_f32 v[180:181], v[130:131], v[142:143] op_sel_hi:[1,0]
	v_add_f32_e32 v198, v176, v177
	v_pk_mul_f32 v[190:191], v[130:131], v[142:143] op_sel:[0,1] op_sel_hi:[1,1]
	v_add_f32_e32 v200, v178, v179
	v_pk_mul_f32 v[188:189], v[132:133], v[142:143] op_sel_hi:[1,0]
	v_add_f32_dpp v198, v198, v198 quad_perm:[1,0,3,2] row_mask:0xf bank_mask:0xf bound_ctrl:1
	v_pk_mul_f32 v[192:193], v[132:133], v[142:143] op_sel:[0,1] op_sel_hi:[1,1]
	v_add_f32_dpp v200, v200, v200 quad_perm:[1,0,3,2] row_mask:0xf bank_mask:0xf bound_ctrl:1
	v_pk_fma_f32 v[2:3], v[2:3], v[122:123], v[180:181]
	v_add_f32_dpp v198, v198, v198 quad_perm:[2,3,0,1] row_mask:0xf bank_mask:0xf bound_ctrl:1
	v_pk_fma_f32 v[6:7], v[6:7], v[122:123], v[190:191]
	v_add_f32_dpp v200, v200, v200 quad_perm:[2,3,0,1] row_mask:0xf bank_mask:0xf bound_ctrl:1
	v_pk_fma_f32 v[4:5], v[4:5], v[124:125], v[188:189]
	v_add_f32_dpp v198, v198, v198 row_half_mirror row_mask:0xf bank_mask:0xf bound_ctrl:1
	v_pk_fma_f32 v[8:9], v[8:9], v[124:125], v[192:193]
	v_add_f32_dpp v200, v200, v200 row_half_mirror row_mask:0xf bank_mask:0xf bound_ctrl:1
	ds_read_b128 v[134:137], v42 offset:31488
	v_add_f32_dpp v198, v198, v198 row_mirror row_mask:0xf bank_mask:0xf bound_ctrl:1
	ds_read_b128 v[130:133], v42 offset:31232
	v_add_f32_dpp v200, v200, v200 row_mirror row_mask:0xf bank_mask:0xf bound_ctrl:1
	ds_read_b32 v142, v43 offset:30720
	ds_read_b32 v143, v43 offset:30736
	v_pk_fma_f32 v[2:3], v[126:127], v[198:199], v[2:3] op_sel_hi:[1,0,1] neg_lo:[0,1,0] neg_hi:[0,1,0]
	v_pk_fma_f32 v[4:5], v[128:129], v[198:199], v[4:5] op_sel_hi:[1,0,1] neg_lo:[0,1,0] neg_hi:[0,1,0]
	v_pk_fma_f32 v[6:7], v[126:127], v[200:201], v[6:7] op_sel_hi:[1,0,1] neg_lo:[0,1,0] neg_hi:[0,1,0]
	v_pk_fma_f32 v[8:9], v[128:129], v[200:201], v[8:9] op_sel_hi:[1,0,1] neg_lo:[0,1,0] neg_hi:[0,1,0]
	ds_read_b128 v[122:125], v42 offset:30720
	v_pk_mul_f32 v[194:195], v[140:141], v[4:5]
	v_pk_mul_f32 v[196:197], v[140:141], v[8:9]
	ds_read_b128 v[126:129], v42 offset:30976
	v_pk_fma_f32 v[194:195], v[138:139], v[2:3], v[194:195]
	v_pk_fma_f32 v[196:197], v[138:139], v[6:7], v[196:197]
	ds_read_b128 v[138:141], v42 offset:31744
	v_add_f32_e32 v12, v194, v195
	v_add_f32_e32 v28, v196, v197
	s_waitcnt lgkmcnt(7)
	v_pk_mul_f32 v[176:177], v[2:3], v[166:167]
	v_pk_mul_f32 v[178:179], v[6:7], v[166:167]
	v_pk_fma_f32 v[176:177], v[4:5], v[168:169], v[176:177]
	v_pk_fma_f32 v[178:179], v[8:9], v[168:169], v[178:179]
	v_pk_mul_f32 v[180:181], v[162:163], v[174:175] op_sel_hi:[1,0]
	v_add_f32_e32 v198, v176, v177
	v_pk_mul_f32 v[190:191], v[162:163], v[174:175] op_sel:[0,1] op_sel_hi:[1,1]
	v_add_f32_e32 v200, v178, v179
	v_pk_mul_f32 v[188:189], v[164:165], v[174:175] op_sel_hi:[1,0]
	v_add_f32_dpp v198, v198, v198 quad_perm:[1,0,3,2] row_mask:0xf bank_mask:0xf bound_ctrl:1
	v_pk_mul_f32 v[192:193], v[164:165], v[174:175] op_sel:[0,1] op_sel_hi:[1,1]
	v_add_f32_dpp v200, v200, v200 quad_perm:[1,0,3,2] row_mask:0xf bank_mask:0xf bound_ctrl:1
	v_pk_fma_f32 v[2:3], v[2:3], v[154:155], v[180:181]
	v_add_f32_dpp v198, v198, v198 quad_perm:[2,3,0,1] row_mask:0xf bank_mask:0xf bound_ctrl:1
	v_pk_fma_f32 v[6:7], v[6:7], v[154:155], v[190:191]
	v_add_f32_dpp v200, v200, v200 quad_perm:[2,3,0,1] row_mask:0xf bank_mask:0xf bound_ctrl:1
	v_pk_fma_f32 v[4:5], v[4:5], v[156:157], v[188:189]
	v_add_f32_dpp v198, v198, v198 row_half_mirror row_mask:0xf bank_mask:0xf bound_ctrl:1
	v_pk_fma_f32 v[8:9], v[8:9], v[156:157], v[192:193]
	v_add_f32_dpp v200, v200, v200 row_half_mirror row_mask:0xf bank_mask:0xf bound_ctrl:1
	ds_read_b128 v[166:169], v42 offset:33024
	v_add_f32_dpp v198, v198, v198 row_mirror row_mask:0xf bank_mask:0xf bound_ctrl:1
	ds_read_b128 v[162:165], v42 offset:32768
	v_add_f32_dpp v200, v200, v200 row_mirror row_mask:0xf bank_mask:0xf bound_ctrl:1
	ds_read_b32 v174, v43 offset:32256
	ds_read_b32 v175, v43 offset:32272
	v_pk_fma_f32 v[2:3], v[158:159], v[198:199], v[2:3] op_sel_hi:[1,0,1] neg_lo:[0,1,0] neg_hi:[0,1,0]
	v_pk_fma_f32 v[4:5], v[160:161], v[198:199], v[4:5] op_sel_hi:[1,0,1] neg_lo:[0,1,0] neg_hi:[0,1,0]
	v_pk_fma_f32 v[6:7], v[158:159], v[200:201], v[6:7] op_sel_hi:[1,0,1] neg_lo:[0,1,0] neg_hi:[0,1,0]
	v_pk_fma_f32 v[8:9], v[160:161], v[200:201], v[8:9] op_sel_hi:[1,0,1] neg_lo:[0,1,0] neg_hi:[0,1,0]
	ds_read_b128 v[154:157], v42 offset:32256
	v_pk_mul_f32 v[194:195], v[172:173], v[4:5]
	v_pk_mul_f32 v[196:197], v[172:173], v[8:9]
	ds_read_b128 v[158:161], v42 offset:32512
	v_pk_fma_f32 v[194:195], v[170:171], v[2:3], v[194:195]
	v_pk_fma_f32 v[196:197], v[170:171], v[6:7], v[196:197]
	ds_read_b128 v[170:173], v42 offset:33280
	v_add_f32_e32 v13, v194, v195
	v_add_f32_e32 v29, v196, v197
	s_waitcnt lgkmcnt(7)
	v_pk_mul_f32 v[176:177], v[2:3], v[134:135]
	v_pk_mul_f32 v[178:179], v[6:7], v[134:135]
	v_pk_fma_f32 v[176:177], v[4:5], v[136:137], v[176:177]
	v_pk_fma_f32 v[178:179], v[8:9], v[136:137], v[178:179]
	v_pk_mul_f32 v[180:181], v[130:131], v[142:143] op_sel_hi:[1,0]
	v_add_f32_e32 v198, v176, v177
	v_pk_mul_f32 v[190:191], v[130:131], v[142:143] op_sel:[0,1] op_sel_hi:[1,1]
	v_add_f32_e32 v200, v178, v179
	v_pk_mul_f32 v[188:189], v[132:133], v[142:143] op_sel_hi:[1,0]
	v_add_f32_dpp v198, v198, v198 quad_perm:[1,0,3,2] row_mask:0xf bank_mask:0xf bound_ctrl:1
	v_pk_mul_f32 v[192:193], v[132:133], v[142:143] op_sel:[0,1] op_sel_hi:[1,1]
	v_add_f32_dpp v200, v200, v200 quad_perm:[1,0,3,2] row_mask:0xf bank_mask:0xf bound_ctrl:1
	v_pk_fma_f32 v[2:3], v[2:3], v[122:123], v[180:181]
	v_add_f32_dpp v198, v198, v198 quad_perm:[2,3,0,1] row_mask:0xf bank_mask:0xf bound_ctrl:1
	v_pk_fma_f32 v[6:7], v[6:7], v[122:123], v[190:191]
	v_add_f32_dpp v200, v200, v200 quad_perm:[2,3,0,1] row_mask:0xf bank_mask:0xf bound_ctrl:1
	v_pk_fma_f32 v[4:5], v[4:5], v[124:125], v[188:189]
	v_add_f32_dpp v198, v198, v198 row_half_mirror row_mask:0xf bank_mask:0xf bound_ctrl:1
	v_pk_fma_f32 v[8:9], v[8:9], v[124:125], v[192:193]
	v_add_f32_dpp v200, v200, v200 row_half_mirror row_mask:0xf bank_mask:0xf bound_ctrl:1
	ds_read_b128 v[134:137], v42 offset:34560
	v_add_f32_dpp v198, v198, v198 row_mirror row_mask:0xf bank_mask:0xf bound_ctrl:1
	ds_read_b128 v[130:133], v42 offset:34304
	v_add_f32_dpp v200, v200, v200 row_mirror row_mask:0xf bank_mask:0xf bound_ctrl:1
	ds_read_b32 v142, v43 offset:33792
	ds_read_b32 v143, v43 offset:33808
	v_pk_fma_f32 v[2:3], v[126:127], v[198:199], v[2:3] op_sel_hi:[1,0,1] neg_lo:[0,1,0] neg_hi:[0,1,0]
	v_pk_fma_f32 v[4:5], v[128:129], v[198:199], v[4:5] op_sel_hi:[1,0,1] neg_lo:[0,1,0] neg_hi:[0,1,0]
	v_pk_fma_f32 v[6:7], v[126:127], v[200:201], v[6:7] op_sel_hi:[1,0,1] neg_lo:[0,1,0] neg_hi:[0,1,0]
	v_pk_fma_f32 v[8:9], v[128:129], v[200:201], v[8:9] op_sel_hi:[1,0,1] neg_lo:[0,1,0] neg_hi:[0,1,0]
	ds_read_b128 v[122:125], v42 offset:33792
	v_pk_mul_f32 v[194:195], v[140:141], v[4:5]
	v_pk_mul_f32 v[196:197], v[140:141], v[8:9]
	ds_read_b128 v[126:129], v42 offset:34048
	v_pk_fma_f32 v[194:195], v[138:139], v[2:3], v[194:195]
	v_pk_fma_f32 v[196:197], v[138:139], v[6:7], v[196:197]
	ds_read_b128 v[138:141], v42 offset:34816
	v_add_f32_e32 v14, v194, v195
	v_add_f32_e32 v30, v196, v197
	s_waitcnt lgkmcnt(7)
	v_pk_mul_f32 v[176:177], v[2:3], v[166:167]
	v_pk_mul_f32 v[178:179], v[6:7], v[166:167]
	v_pk_fma_f32 v[176:177], v[4:5], v[168:169], v[176:177]
	v_pk_fma_f32 v[178:179], v[8:9], v[168:169], v[178:179]
	v_pk_mul_f32 v[180:181], v[162:163], v[174:175] op_sel_hi:[1,0]
	v_add_f32_e32 v198, v176, v177
	v_pk_mul_f32 v[190:191], v[162:163], v[174:175] op_sel:[0,1] op_sel_hi:[1,1]
	v_add_f32_e32 v200, v178, v179
	v_pk_mul_f32 v[188:189], v[164:165], v[174:175] op_sel_hi:[1,0]
	v_add_f32_dpp v198, v198, v198 quad_perm:[1,0,3,2] row_mask:0xf bank_mask:0xf bound_ctrl:1
	v_pk_mul_f32 v[192:193], v[164:165], v[174:175] op_sel:[0,1] op_sel_hi:[1,1]
	v_add_f32_dpp v200, v200, v200 quad_perm:[1,0,3,2] row_mask:0xf bank_mask:0xf bound_ctrl:1
	v_pk_fma_f32 v[2:3], v[2:3], v[154:155], v[180:181]
	v_add_f32_dpp v198, v198, v198 quad_perm:[2,3,0,1] row_mask:0xf bank_mask:0xf bound_ctrl:1
	v_pk_fma_f32 v[6:7], v[6:7], v[154:155], v[190:191]
	v_add_f32_dpp v200, v200, v200 quad_perm:[2,3,0,1] row_mask:0xf bank_mask:0xf bound_ctrl:1
	v_pk_fma_f32 v[4:5], v[4:5], v[156:157], v[188:189]
	v_add_f32_dpp v198, v198, v198 row_half_mirror row_mask:0xf bank_mask:0xf bound_ctrl:1
	v_pk_fma_f32 v[8:9], v[8:9], v[156:157], v[192:193]
	v_add_f32_dpp v200, v200, v200 row_half_mirror row_mask:0xf bank_mask:0xf bound_ctrl:1
	ds_read_b128 v[166:169], v42 offset:36096
	v_add_f32_dpp v198, v198, v198 row_mirror row_mask:0xf bank_mask:0xf bound_ctrl:1
	ds_read_b128 v[162:165], v42 offset:35840
	v_add_f32_dpp v200, v200, v200 row_mirror row_mask:0xf bank_mask:0xf bound_ctrl:1
	ds_read_b32 v174, v43 offset:35328
	ds_read_b32 v175, v43 offset:35344
	v_pk_fma_f32 v[2:3], v[158:159], v[198:199], v[2:3] op_sel_hi:[1,0,1] neg_lo:[0,1,0] neg_hi:[0,1,0]
	v_pk_fma_f32 v[4:5], v[160:161], v[198:199], v[4:5] op_sel_hi:[1,0,1] neg_lo:[0,1,0] neg_hi:[0,1,0]
	v_pk_fma_f32 v[6:7], v[158:159], v[200:201], v[6:7] op_sel_hi:[1,0,1] neg_lo:[0,1,0] neg_hi:[0,1,0]
	v_pk_fma_f32 v[8:9], v[160:161], v[200:201], v[8:9] op_sel_hi:[1,0,1] neg_lo:[0,1,0] neg_hi:[0,1,0]
	ds_read_b128 v[154:157], v42 offset:35328
	v_pk_mul_f32 v[194:195], v[172:173], v[4:5]
	v_pk_mul_f32 v[196:197], v[172:173], v[8:9]
	ds_read_b128 v[158:161], v42 offset:35584
	v_pk_fma_f32 v[194:195], v[170:171], v[2:3], v[194:195]
	v_pk_fma_f32 v[196:197], v[170:171], v[6:7], v[196:197]
	ds_read_b128 v[170:173], v42 offset:36352
	v_add_f32_e32 v15, v194, v195
	v_add_f32_e32 v31, v196, v197
	s_waitcnt lgkmcnt(7)
	v_pk_mul_f32 v[176:177], v[2:3], v[134:135]
	v_pk_mul_f32 v[178:179], v[6:7], v[134:135]
	v_pk_fma_f32 v[176:177], v[4:5], v[136:137], v[176:177]
	v_pk_fma_f32 v[178:179], v[8:9], v[136:137], v[178:179]
	v_pk_mul_f32 v[180:181], v[130:131], v[142:143] op_sel_hi:[1,0]
	v_add_f32_e32 v198, v176, v177
	v_pk_mul_f32 v[190:191], v[130:131], v[142:143] op_sel:[0,1] op_sel_hi:[1,1]
	v_add_f32_e32 v200, v178, v179
	v_pk_mul_f32 v[188:189], v[132:133], v[142:143] op_sel_hi:[1,0]
	v_add_f32_dpp v198, v198, v198 quad_perm:[1,0,3,2] row_mask:0xf bank_mask:0xf bound_ctrl:1
	v_pk_mul_f32 v[192:193], v[132:133], v[142:143] op_sel:[0,1] op_sel_hi:[1,1]
	v_add_f32_dpp v200, v200, v200 quad_perm:[1,0,3,2] row_mask:0xf bank_mask:0xf bound_ctrl:1
	v_pk_fma_f32 v[2:3], v[2:3], v[122:123], v[180:181]
	v_add_f32_dpp v198, v198, v198 quad_perm:[2,3,0,1] row_mask:0xf bank_mask:0xf bound_ctrl:1
	v_pk_fma_f32 v[6:7], v[6:7], v[122:123], v[190:191]
	v_add_f32_dpp v200, v200, v200 quad_perm:[2,3,0,1] row_mask:0xf bank_mask:0xf bound_ctrl:1
	v_pk_fma_f32 v[4:5], v[4:5], v[124:125], v[188:189]
	v_add_f32_dpp v198, v198, v198 row_half_mirror row_mask:0xf bank_mask:0xf bound_ctrl:1
	v_pk_fma_f32 v[8:9], v[8:9], v[124:125], v[192:193]
	v_add_f32_dpp v200, v200, v200 row_half_mirror row_mask:0xf bank_mask:0xf bound_ctrl:1
	ds_read_b128 v[134:137], v42 offset:37632
	v_add_f32_dpp v198, v198, v198 row_mirror row_mask:0xf bank_mask:0xf bound_ctrl:1
	ds_read_b128 v[130:133], v42 offset:37376
	v_add_f32_dpp v200, v200, v200 row_mirror row_mask:0xf bank_mask:0xf bound_ctrl:1
	ds_read_b32 v142, v43 offset:36864
	ds_read_b32 v143, v43 offset:36880
	v_pk_fma_f32 v[2:3], v[126:127], v[198:199], v[2:3] op_sel_hi:[1,0,1] neg_lo:[0,1,0] neg_hi:[0,1,0]
	v_pk_fma_f32 v[4:5], v[128:129], v[198:199], v[4:5] op_sel_hi:[1,0,1] neg_lo:[0,1,0] neg_hi:[0,1,0]
	v_pk_fma_f32 v[6:7], v[126:127], v[200:201], v[6:7] op_sel_hi:[1,0,1] neg_lo:[0,1,0] neg_hi:[0,1,0]
	v_pk_fma_f32 v[8:9], v[128:129], v[200:201], v[8:9] op_sel_hi:[1,0,1] neg_lo:[0,1,0] neg_hi:[0,1,0]
	ds_read_b128 v[122:125], v42 offset:36864
	v_pk_mul_f32 v[194:195], v[140:141], v[4:5]
	v_pk_mul_f32 v[196:197], v[140:141], v[8:9]
	ds_read_b128 v[126:129], v42 offset:37120
	v_pk_fma_f32 v[194:195], v[138:139], v[2:3], v[194:195]
	v_pk_fma_f32 v[196:197], v[138:139], v[6:7], v[196:197]
	ds_read_b128 v[138:141], v42 offset:37888
	v_add_f32_e32 v16, v194, v195
	v_add_f32_e32 v32, v196, v197
	s_waitcnt lgkmcnt(7)
	v_pk_mul_f32 v[176:177], v[2:3], v[166:167]
	v_pk_mul_f32 v[178:179], v[6:7], v[166:167]
	v_pk_fma_f32 v[176:177], v[4:5], v[168:169], v[176:177]
	v_pk_fma_f32 v[178:179], v[8:9], v[168:169], v[178:179]
	v_pk_mul_f32 v[180:181], v[162:163], v[174:175] op_sel_hi:[1,0]
	v_add_f32_e32 v198, v176, v177
	v_pk_mul_f32 v[190:191], v[162:163], v[174:175] op_sel:[0,1] op_sel_hi:[1,1]
	v_add_f32_e32 v200, v178, v179
	v_pk_mul_f32 v[188:189], v[164:165], v[174:175] op_sel_hi:[1,0]
	v_add_f32_dpp v198, v198, v198 quad_perm:[1,0,3,2] row_mask:0xf bank_mask:0xf bound_ctrl:1
	v_pk_mul_f32 v[192:193], v[164:165], v[174:175] op_sel:[0,1] op_sel_hi:[1,1]
	v_add_f32_dpp v200, v200, v200 quad_perm:[1,0,3,2] row_mask:0xf bank_mask:0xf bound_ctrl:1
	v_pk_fma_f32 v[2:3], v[2:3], v[154:155], v[180:181]
	v_add_f32_dpp v198, v198, v198 quad_perm:[2,3,0,1] row_mask:0xf bank_mask:0xf bound_ctrl:1
	v_pk_fma_f32 v[6:7], v[6:7], v[154:155], v[190:191]
	v_add_f32_dpp v200, v200, v200 quad_perm:[2,3,0,1] row_mask:0xf bank_mask:0xf bound_ctrl:1
	v_pk_fma_f32 v[4:5], v[4:5], v[156:157], v[188:189]
	v_add_f32_dpp v198, v198, v198 row_half_mirror row_mask:0xf bank_mask:0xf bound_ctrl:1
	v_pk_fma_f32 v[8:9], v[8:9], v[156:157], v[192:193]
	v_add_f32_dpp v200, v200, v200 row_half_mirror row_mask:0xf bank_mask:0xf bound_ctrl:1
	ds_read_b128 v[166:169], v42 offset:39168
	v_add_f32_dpp v198, v198, v198 row_mirror row_mask:0xf bank_mask:0xf bound_ctrl:1
	ds_read_b128 v[162:165], v42 offset:38912
	v_add_f32_dpp v200, v200, v200 row_mirror row_mask:0xf bank_mask:0xf bound_ctrl:1
	ds_read_b32 v174, v43 offset:38400
	ds_read_b32 v175, v43 offset:38416
	v_pk_fma_f32 v[2:3], v[158:159], v[198:199], v[2:3] op_sel_hi:[1,0,1] neg_lo:[0,1,0] neg_hi:[0,1,0]
	v_pk_fma_f32 v[4:5], v[160:161], v[198:199], v[4:5] op_sel_hi:[1,0,1] neg_lo:[0,1,0] neg_hi:[0,1,0]
	v_pk_fma_f32 v[6:7], v[158:159], v[200:201], v[6:7] op_sel_hi:[1,0,1] neg_lo:[0,1,0] neg_hi:[0,1,0]
	v_pk_fma_f32 v[8:9], v[160:161], v[200:201], v[8:9] op_sel_hi:[1,0,1] neg_lo:[0,1,0] neg_hi:[0,1,0]
	ds_read_b128 v[154:157], v42 offset:38400
	v_pk_mul_f32 v[194:195], v[172:173], v[4:5]
	v_pk_mul_f32 v[196:197], v[172:173], v[8:9]
	ds_read_b128 v[158:161], v42 offset:38656
	v_pk_fma_f32 v[194:195], v[170:171], v[2:3], v[194:195]
	v_pk_fma_f32 v[196:197], v[170:171], v[6:7], v[196:197]
	ds_read_b128 v[170:173], v42 offset:39424
	v_add_f32_e32 v17, v194, v195
	v_add_f32_e32 v33, v196, v197
	s_waitcnt lgkmcnt(7)
	v_pk_mul_f32 v[176:177], v[2:3], v[134:135]
	v_pk_mul_f32 v[178:179], v[6:7], v[134:135]
	v_pk_fma_f32 v[176:177], v[4:5], v[136:137], v[176:177]
	v_pk_fma_f32 v[178:179], v[8:9], v[136:137], v[178:179]
	v_pk_mul_f32 v[180:181], v[130:131], v[142:143] op_sel_hi:[1,0]
	v_add_f32_e32 v198, v176, v177
	v_pk_mul_f32 v[190:191], v[130:131], v[142:143] op_sel:[0,1] op_sel_hi:[1,1]
	v_add_f32_e32 v200, v178, v179
	v_pk_mul_f32 v[188:189], v[132:133], v[142:143] op_sel_hi:[1,0]
	v_add_f32_dpp v198, v198, v198 quad_perm:[1,0,3,2] row_mask:0xf bank_mask:0xf bound_ctrl:1
	v_pk_mul_f32 v[192:193], v[132:133], v[142:143] op_sel:[0,1] op_sel_hi:[1,1]
	v_add_f32_dpp v200, v200, v200 quad_perm:[1,0,3,2] row_mask:0xf bank_mask:0xf bound_ctrl:1
	v_pk_fma_f32 v[2:3], v[2:3], v[122:123], v[180:181]
	v_add_f32_dpp v198, v198, v198 quad_perm:[2,3,0,1] row_mask:0xf bank_mask:0xf bound_ctrl:1
	v_pk_fma_f32 v[6:7], v[6:7], v[122:123], v[190:191]
	v_add_f32_dpp v200, v200, v200 quad_perm:[2,3,0,1] row_mask:0xf bank_mask:0xf bound_ctrl:1
	v_pk_fma_f32 v[4:5], v[4:5], v[124:125], v[188:189]
	v_add_f32_dpp v198, v198, v198 row_half_mirror row_mask:0xf bank_mask:0xf bound_ctrl:1
	v_pk_fma_f32 v[8:9], v[8:9], v[124:125], v[192:193]
	v_add_f32_dpp v200, v200, v200 row_half_mirror row_mask:0xf bank_mask:0xf bound_ctrl:1
	ds_read_b128 v[134:137], v42 offset:40704
	v_add_f32_dpp v198, v198, v198 row_mirror row_mask:0xf bank_mask:0xf bound_ctrl:1
	ds_read_b128 v[130:133], v42 offset:40448
	v_add_f32_dpp v200, v200, v200 row_mirror row_mask:0xf bank_mask:0xf bound_ctrl:1
	ds_read_b32 v142, v43 offset:39936
	ds_read_b32 v143, v43 offset:39952
	v_pk_fma_f32 v[2:3], v[126:127], v[198:199], v[2:3] op_sel_hi:[1,0,1] neg_lo:[0,1,0] neg_hi:[0,1,0]
	v_pk_fma_f32 v[4:5], v[128:129], v[198:199], v[4:5] op_sel_hi:[1,0,1] neg_lo:[0,1,0] neg_hi:[0,1,0]
	v_pk_fma_f32 v[6:7], v[126:127], v[200:201], v[6:7] op_sel_hi:[1,0,1] neg_lo:[0,1,0] neg_hi:[0,1,0]
	v_pk_fma_f32 v[8:9], v[128:129], v[200:201], v[8:9] op_sel_hi:[1,0,1] neg_lo:[0,1,0] neg_hi:[0,1,0]
	ds_read_b128 v[122:125], v42 offset:39936
	v_pk_mul_f32 v[194:195], v[140:141], v[4:5]
	v_pk_mul_f32 v[196:197], v[140:141], v[8:9]
	ds_read_b128 v[126:129], v42 offset:40192
	v_pk_fma_f32 v[194:195], v[138:139], v[2:3], v[194:195]
	v_pk_fma_f32 v[196:197], v[138:139], v[6:7], v[196:197]
	ds_read_b128 v[138:141], v42 offset:40960
	v_add_f32_e32 v18, v194, v195
	v_add_f32_e32 v34, v196, v197
	s_waitcnt lgkmcnt(7)
	v_pk_mul_f32 v[176:177], v[2:3], v[166:167]
	v_pk_mul_f32 v[178:179], v[6:7], v[166:167]
	v_pk_fma_f32 v[176:177], v[4:5], v[168:169], v[176:177]
	v_pk_fma_f32 v[178:179], v[8:9], v[168:169], v[178:179]
	v_pk_mul_f32 v[180:181], v[162:163], v[174:175] op_sel_hi:[1,0]
	v_add_f32_e32 v198, v176, v177
	v_pk_mul_f32 v[190:191], v[162:163], v[174:175] op_sel:[0,1] op_sel_hi:[1,1]
	v_add_f32_e32 v200, v178, v179
	v_pk_mul_f32 v[188:189], v[164:165], v[174:175] op_sel_hi:[1,0]
	v_add_f32_dpp v198, v198, v198 quad_perm:[1,0,3,2] row_mask:0xf bank_mask:0xf bound_ctrl:1
	v_pk_mul_f32 v[192:193], v[164:165], v[174:175] op_sel:[0,1] op_sel_hi:[1,1]
	v_add_f32_dpp v200, v200, v200 quad_perm:[1,0,3,2] row_mask:0xf bank_mask:0xf bound_ctrl:1
	v_pk_fma_f32 v[2:3], v[2:3], v[154:155], v[180:181]
	v_add_f32_dpp v198, v198, v198 quad_perm:[2,3,0,1] row_mask:0xf bank_mask:0xf bound_ctrl:1
	v_pk_fma_f32 v[6:7], v[6:7], v[154:155], v[190:191]
	v_add_f32_dpp v200, v200, v200 quad_perm:[2,3,0,1] row_mask:0xf bank_mask:0xf bound_ctrl:1
	v_pk_fma_f32 v[4:5], v[4:5], v[156:157], v[188:189]
	v_add_f32_dpp v198, v198, v198 row_half_mirror row_mask:0xf bank_mask:0xf bound_ctrl:1
	v_pk_fma_f32 v[8:9], v[8:9], v[156:157], v[192:193]
	v_add_f32_dpp v200, v200, v200 row_half_mirror row_mask:0xf bank_mask:0xf bound_ctrl:1
	ds_read_b128 v[166:169], v42 offset:42240
	v_add_f32_dpp v198, v198, v198 row_mirror row_mask:0xf bank_mask:0xf bound_ctrl:1
	ds_read_b128 v[162:165], v42 offset:41984
	v_add_f32_dpp v200, v200, v200 row_mirror row_mask:0xf bank_mask:0xf bound_ctrl:1
	ds_read_b32 v174, v43 offset:41472
	ds_read_b32 v175, v43 offset:41488
	v_pk_fma_f32 v[2:3], v[158:159], v[198:199], v[2:3] op_sel_hi:[1,0,1] neg_lo:[0,1,0] neg_hi:[0,1,0]
	v_pk_fma_f32 v[4:5], v[160:161], v[198:199], v[4:5] op_sel_hi:[1,0,1] neg_lo:[0,1,0] neg_hi:[0,1,0]
	v_pk_fma_f32 v[6:7], v[158:159], v[200:201], v[6:7] op_sel_hi:[1,0,1] neg_lo:[0,1,0] neg_hi:[0,1,0]
	v_pk_fma_f32 v[8:9], v[160:161], v[200:201], v[8:9] op_sel_hi:[1,0,1] neg_lo:[0,1,0] neg_hi:[0,1,0]
	ds_read_b128 v[154:157], v42 offset:41472
	v_pk_mul_f32 v[194:195], v[172:173], v[4:5]
	v_pk_mul_f32 v[196:197], v[172:173], v[8:9]
	ds_read_b128 v[158:161], v42 offset:41728
	v_pk_fma_f32 v[194:195], v[170:171], v[2:3], v[194:195]
	v_pk_fma_f32 v[196:197], v[170:171], v[6:7], v[196:197]
	ds_read_b128 v[170:173], v42 offset:42496
	v_add_f32_e32 v19, v194, v195
	v_add_f32_e32 v35, v196, v197
	s_waitcnt lgkmcnt(7)
	v_pk_mul_f32 v[176:177], v[2:3], v[134:135]
	v_pk_mul_f32 v[178:179], v[6:7], v[134:135]
	v_pk_fma_f32 v[176:177], v[4:5], v[136:137], v[176:177]
	v_pk_fma_f32 v[178:179], v[8:9], v[136:137], v[178:179]
	v_pk_mul_f32 v[180:181], v[130:131], v[142:143] op_sel_hi:[1,0]
	v_add_f32_e32 v198, v176, v177
	v_pk_mul_f32 v[190:191], v[130:131], v[142:143] op_sel:[0,1] op_sel_hi:[1,1]
	v_add_f32_e32 v200, v178, v179
	v_pk_mul_f32 v[188:189], v[132:133], v[142:143] op_sel_hi:[1,0]
	v_add_f32_dpp v198, v198, v198 quad_perm:[1,0,3,2] row_mask:0xf bank_mask:0xf bound_ctrl:1
	v_pk_mul_f32 v[192:193], v[132:133], v[142:143] op_sel:[0,1] op_sel_hi:[1,1]
	v_add_f32_dpp v200, v200, v200 quad_perm:[1,0,3,2] row_mask:0xf bank_mask:0xf bound_ctrl:1
	v_pk_fma_f32 v[2:3], v[2:3], v[122:123], v[180:181]
	v_add_f32_dpp v198, v198, v198 quad_perm:[2,3,0,1] row_mask:0xf bank_mask:0xf bound_ctrl:1
	v_pk_fma_f32 v[6:7], v[6:7], v[122:123], v[190:191]
	v_add_f32_dpp v200, v200, v200 quad_perm:[2,3,0,1] row_mask:0xf bank_mask:0xf bound_ctrl:1
	v_pk_fma_f32 v[4:5], v[4:5], v[124:125], v[188:189]
	v_add_f32_dpp v198, v198, v198 row_half_mirror row_mask:0xf bank_mask:0xf bound_ctrl:1
	v_pk_fma_f32 v[8:9], v[8:9], v[124:125], v[192:193]
	v_add_f32_dpp v200, v200, v200 row_half_mirror row_mask:0xf bank_mask:0xf bound_ctrl:1
	ds_read_b128 v[134:137], v42 offset:43776
	v_add_f32_dpp v198, v198, v198 row_mirror row_mask:0xf bank_mask:0xf bound_ctrl:1
	ds_read_b128 v[130:133], v42 offset:43520
	v_add_f32_dpp v200, v200, v200 row_mirror row_mask:0xf bank_mask:0xf bound_ctrl:1
	ds_read_b32 v142, v43 offset:43008
	ds_read_b32 v143, v43 offset:43024
	v_pk_fma_f32 v[2:3], v[126:127], v[198:199], v[2:3] op_sel_hi:[1,0,1] neg_lo:[0,1,0] neg_hi:[0,1,0]
	v_pk_fma_f32 v[4:5], v[128:129], v[198:199], v[4:5] op_sel_hi:[1,0,1] neg_lo:[0,1,0] neg_hi:[0,1,0]
	v_pk_fma_f32 v[6:7], v[126:127], v[200:201], v[6:7] op_sel_hi:[1,0,1] neg_lo:[0,1,0] neg_hi:[0,1,0]
	v_pk_fma_f32 v[8:9], v[128:129], v[200:201], v[8:9] op_sel_hi:[1,0,1] neg_lo:[0,1,0] neg_hi:[0,1,0]
	ds_read_b128 v[122:125], v42 offset:43008
	v_pk_mul_f32 v[194:195], v[140:141], v[4:5]
	v_pk_mul_f32 v[196:197], v[140:141], v[8:9]
	ds_read_b128 v[126:129], v42 offset:43264
	v_pk_fma_f32 v[194:195], v[138:139], v[2:3], v[194:195]
	v_pk_fma_f32 v[196:197], v[138:139], v[6:7], v[196:197]
	ds_read_b128 v[138:141], v42 offset:44032
	v_add_f32_e32 v20, v194, v195
	v_add_f32_e32 v36, v196, v197
	s_waitcnt lgkmcnt(7)
	v_pk_mul_f32 v[176:177], v[2:3], v[166:167]
	v_pk_mul_f32 v[178:179], v[6:7], v[166:167]
	v_pk_fma_f32 v[176:177], v[4:5], v[168:169], v[176:177]
	v_pk_fma_f32 v[178:179], v[8:9], v[168:169], v[178:179]
	v_pk_mul_f32 v[180:181], v[162:163], v[174:175] op_sel_hi:[1,0]
	v_add_f32_e32 v198, v176, v177
	v_pk_mul_f32 v[190:191], v[162:163], v[174:175] op_sel:[0,1] op_sel_hi:[1,1]
	v_add_f32_e32 v200, v178, v179
	v_pk_mul_f32 v[188:189], v[164:165], v[174:175] op_sel_hi:[1,0]
	v_add_f32_dpp v198, v198, v198 quad_perm:[1,0,3,2] row_mask:0xf bank_mask:0xf bound_ctrl:1
	v_pk_mul_f32 v[192:193], v[164:165], v[174:175] op_sel:[0,1] op_sel_hi:[1,1]
	v_add_f32_dpp v200, v200, v200 quad_perm:[1,0,3,2] row_mask:0xf bank_mask:0xf bound_ctrl:1
	v_pk_fma_f32 v[2:3], v[2:3], v[154:155], v[180:181]
	v_add_f32_dpp v198, v198, v198 quad_perm:[2,3,0,1] row_mask:0xf bank_mask:0xf bound_ctrl:1
	v_pk_fma_f32 v[6:7], v[6:7], v[154:155], v[190:191]
	v_add_f32_dpp v200, v200, v200 quad_perm:[2,3,0,1] row_mask:0xf bank_mask:0xf bound_ctrl:1
	v_pk_fma_f32 v[4:5], v[4:5], v[156:157], v[188:189]
	v_add_f32_dpp v198, v198, v198 row_half_mirror row_mask:0xf bank_mask:0xf bound_ctrl:1
	v_pk_fma_f32 v[8:9], v[8:9], v[156:157], v[192:193]
	v_add_f32_dpp v200, v200, v200 row_half_mirror row_mask:0xf bank_mask:0xf bound_ctrl:1
	ds_read_b128 v[166:169], v42 offset:45312
	v_add_f32_dpp v198, v198, v198 row_mirror row_mask:0xf bank_mask:0xf bound_ctrl:1
	ds_read_b128 v[162:165], v42 offset:45056
	v_add_f32_dpp v200, v200, v200 row_mirror row_mask:0xf bank_mask:0xf bound_ctrl:1
	ds_read_b32 v174, v43 offset:44544
	ds_read_b32 v175, v43 offset:44560
	v_pk_fma_f32 v[2:3], v[158:159], v[198:199], v[2:3] op_sel_hi:[1,0,1] neg_lo:[0,1,0] neg_hi:[0,1,0]
	v_pk_fma_f32 v[4:5], v[160:161], v[198:199], v[4:5] op_sel_hi:[1,0,1] neg_lo:[0,1,0] neg_hi:[0,1,0]
	v_pk_fma_f32 v[6:7], v[158:159], v[200:201], v[6:7] op_sel_hi:[1,0,1] neg_lo:[0,1,0] neg_hi:[0,1,0]
	v_pk_fma_f32 v[8:9], v[160:161], v[200:201], v[8:9] op_sel_hi:[1,0,1] neg_lo:[0,1,0] neg_hi:[0,1,0]
	ds_read_b128 v[154:157], v42 offset:44544
	v_pk_mul_f32 v[194:195], v[172:173], v[4:5]
	v_pk_mul_f32 v[196:197], v[172:173], v[8:9]
	ds_read_b128 v[158:161], v42 offset:44800
	v_pk_fma_f32 v[194:195], v[170:171], v[2:3], v[194:195]
	v_pk_fma_f32 v[196:197], v[170:171], v[6:7], v[196:197]
	ds_read_b128 v[170:173], v42 offset:45568
	v_add_f32_e32 v21, v194, v195
	v_add_f32_e32 v37, v196, v197
	s_waitcnt lgkmcnt(7)
	v_pk_mul_f32 v[176:177], v[2:3], v[134:135]
	v_pk_mul_f32 v[178:179], v[6:7], v[134:135]
	v_pk_fma_f32 v[176:177], v[4:5], v[136:137], v[176:177]
	v_pk_fma_f32 v[178:179], v[8:9], v[136:137], v[178:179]
	v_pk_mul_f32 v[180:181], v[130:131], v[142:143] op_sel_hi:[1,0]
	v_add_f32_e32 v198, v176, v177
	v_pk_mul_f32 v[190:191], v[130:131], v[142:143] op_sel:[0,1] op_sel_hi:[1,1]
	v_add_f32_e32 v200, v178, v179
	v_pk_mul_f32 v[188:189], v[132:133], v[142:143] op_sel_hi:[1,0]
	v_add_f32_dpp v198, v198, v198 quad_perm:[1,0,3,2] row_mask:0xf bank_mask:0xf bound_ctrl:1
	v_pk_mul_f32 v[192:193], v[132:133], v[142:143] op_sel:[0,1] op_sel_hi:[1,1]
	v_add_f32_dpp v200, v200, v200 quad_perm:[1,0,3,2] row_mask:0xf bank_mask:0xf bound_ctrl:1
	v_pk_fma_f32 v[2:3], v[2:3], v[122:123], v[180:181]
	v_add_f32_dpp v198, v198, v198 quad_perm:[2,3,0,1] row_mask:0xf bank_mask:0xf bound_ctrl:1
	v_pk_fma_f32 v[6:7], v[6:7], v[122:123], v[190:191]
	v_add_f32_dpp v200, v200, v200 quad_perm:[2,3,0,1] row_mask:0xf bank_mask:0xf bound_ctrl:1
	v_pk_fma_f32 v[4:5], v[4:5], v[124:125], v[188:189]
	v_add_f32_dpp v198, v198, v198 row_half_mirror row_mask:0xf bank_mask:0xf bound_ctrl:1
	v_pk_fma_f32 v[8:9], v[8:9], v[124:125], v[192:193]
	v_add_f32_dpp v200, v200, v200 row_half_mirror row_mask:0xf bank_mask:0xf bound_ctrl:1
	ds_read_b128 v[134:137], v42 offset:46848
	v_add_f32_dpp v198, v198, v198 row_mirror row_mask:0xf bank_mask:0xf bound_ctrl:1
	ds_read_b128 v[130:133], v42 offset:46592
	v_add_f32_dpp v200, v200, v200 row_mirror row_mask:0xf bank_mask:0xf bound_ctrl:1
	ds_read_b32 v142, v43 offset:46080
	ds_read_b32 v143, v43 offset:46096
	v_pk_fma_f32 v[2:3], v[126:127], v[198:199], v[2:3] op_sel_hi:[1,0,1] neg_lo:[0,1,0] neg_hi:[0,1,0]
	v_pk_fma_f32 v[4:5], v[128:129], v[198:199], v[4:5] op_sel_hi:[1,0,1] neg_lo:[0,1,0] neg_hi:[0,1,0]
	v_pk_fma_f32 v[6:7], v[126:127], v[200:201], v[6:7] op_sel_hi:[1,0,1] neg_lo:[0,1,0] neg_hi:[0,1,0]
	v_pk_fma_f32 v[8:9], v[128:129], v[200:201], v[8:9] op_sel_hi:[1,0,1] neg_lo:[0,1,0] neg_hi:[0,1,0]
	ds_read_b128 v[122:125], v42 offset:46080
	v_pk_mul_f32 v[194:195], v[140:141], v[4:5]
	v_pk_mul_f32 v[196:197], v[140:141], v[8:9]
	ds_read_b128 v[126:129], v42 offset:46336
	v_pk_fma_f32 v[194:195], v[138:139], v[2:3], v[194:195]
	v_pk_fma_f32 v[196:197], v[138:139], v[6:7], v[196:197]
	ds_read_b128 v[138:141], v42 offset:47104
	v_add_f32_e32 v22, v194, v195
	v_add_f32_e32 v38, v196, v197
	s_waitcnt lgkmcnt(7)
	v_pk_mul_f32 v[176:177], v[2:3], v[166:167]
	v_pk_mul_f32 v[178:179], v[6:7], v[166:167]
	v_pk_fma_f32 v[176:177], v[4:5], v[168:169], v[176:177]
	v_pk_fma_f32 v[178:179], v[8:9], v[168:169], v[178:179]
	v_pk_mul_f32 v[180:181], v[162:163], v[174:175] op_sel_hi:[1,0]
	v_add_f32_e32 v198, v176, v177
	v_pk_mul_f32 v[190:191], v[162:163], v[174:175] op_sel:[0,1] op_sel_hi:[1,1]
	v_add_f32_e32 v200, v178, v179
	v_pk_mul_f32 v[188:189], v[164:165], v[174:175] op_sel_hi:[1,0]
	v_add_f32_dpp v198, v198, v198 quad_perm:[1,0,3,2] row_mask:0xf bank_mask:0xf bound_ctrl:1
	v_pk_mul_f32 v[192:193], v[164:165], v[174:175] op_sel:[0,1] op_sel_hi:[1,1]
	v_add_f32_dpp v200, v200, v200 quad_perm:[1,0,3,2] row_mask:0xf bank_mask:0xf bound_ctrl:1
	v_pk_fma_f32 v[2:3], v[2:3], v[154:155], v[180:181]
	v_add_f32_dpp v198, v198, v198 quad_perm:[2,3,0,1] row_mask:0xf bank_mask:0xf bound_ctrl:1
	v_pk_fma_f32 v[6:7], v[6:7], v[154:155], v[190:191]
	v_add_f32_dpp v200, v200, v200 quad_perm:[2,3,0,1] row_mask:0xf bank_mask:0xf bound_ctrl:1
	v_pk_fma_f32 v[4:5], v[4:5], v[156:157], v[188:189]
	v_add_f32_dpp v198, v198, v198 row_half_mirror row_mask:0xf bank_mask:0xf bound_ctrl:1
	v_pk_fma_f32 v[8:9], v[8:9], v[156:157], v[192:193]
	v_add_f32_dpp v200, v200, v200 row_half_mirror row_mask:0xf bank_mask:0xf bound_ctrl:1
	ds_read_b128 v[166:169], v42 offset:48384
	v_add_f32_dpp v198, v198, v198 row_mirror row_mask:0xf bank_mask:0xf bound_ctrl:1
	ds_read_b128 v[162:165], v42 offset:48128
	v_add_f32_dpp v200, v200, v200 row_mirror row_mask:0xf bank_mask:0xf bound_ctrl:1
	ds_read_b32 v174, v43 offset:47616
	ds_read_b32 v175, v43 offset:47632
	v_pk_fma_f32 v[2:3], v[158:159], v[198:199], v[2:3] op_sel_hi:[1,0,1] neg_lo:[0,1,0] neg_hi:[0,1,0]
	v_pk_fma_f32 v[4:5], v[160:161], v[198:199], v[4:5] op_sel_hi:[1,0,1] neg_lo:[0,1,0] neg_hi:[0,1,0]
	v_pk_fma_f32 v[6:7], v[158:159], v[200:201], v[6:7] op_sel_hi:[1,0,1] neg_lo:[0,1,0] neg_hi:[0,1,0]
	v_pk_fma_f32 v[8:9], v[160:161], v[200:201], v[8:9] op_sel_hi:[1,0,1] neg_lo:[0,1,0] neg_hi:[0,1,0]
	ds_read_b128 v[154:157], v42 offset:47616
	v_pk_mul_f32 v[194:195], v[172:173], v[4:5]
	v_pk_mul_f32 v[196:197], v[172:173], v[8:9]
	ds_read_b128 v[158:161], v42 offset:47872
	v_pk_fma_f32 v[194:195], v[170:171], v[2:3], v[194:195]
	v_pk_fma_f32 v[196:197], v[170:171], v[6:7], v[196:197]
	ds_read_b128 v[170:173], v42 offset:48640
	v_add_f32_e32 v23, v194, v195
	v_add_f32_e32 v39, v196, v197
	s_waitcnt lgkmcnt(7)
	v_pk_mul_f32 v[176:177], v[2:3], v[134:135]
	v_pk_mul_f32 v[178:179], v[6:7], v[134:135]
	v_pk_fma_f32 v[176:177], v[4:5], v[136:137], v[176:177]
	v_pk_fma_f32 v[178:179], v[8:9], v[136:137], v[178:179]
	v_pk_mul_f32 v[180:181], v[130:131], v[142:143] op_sel_hi:[1,0]
	v_add_f32_e32 v198, v176, v177
	v_pk_mul_f32 v[190:191], v[130:131], v[142:143] op_sel:[0,1] op_sel_hi:[1,1]
	v_add_f32_e32 v200, v178, v179
	v_pk_mul_f32 v[188:189], v[132:133], v[142:143] op_sel_hi:[1,0]
	v_add_f32_dpp v198, v198, v198 quad_perm:[1,0,3,2] row_mask:0xf bank_mask:0xf bound_ctrl:1
	v_pk_mul_f32 v[192:193], v[132:133], v[142:143] op_sel:[0,1] op_sel_hi:[1,1]
	v_add_f32_dpp v200, v200, v200 quad_perm:[1,0,3,2] row_mask:0xf bank_mask:0xf bound_ctrl:1
	v_pk_fma_f32 v[2:3], v[2:3], v[122:123], v[180:181]
	v_add_f32_dpp v198, v198, v198 quad_perm:[2,3,0,1] row_mask:0xf bank_mask:0xf bound_ctrl:1
	v_pk_fma_f32 v[6:7], v[6:7], v[122:123], v[190:191]
	v_add_f32_dpp v200, v200, v200 quad_perm:[2,3,0,1] row_mask:0xf bank_mask:0xf bound_ctrl:1
	v_pk_fma_f32 v[4:5], v[4:5], v[124:125], v[188:189]
	v_add_f32_dpp v198, v198, v198 row_half_mirror row_mask:0xf bank_mask:0xf bound_ctrl:1
	v_pk_fma_f32 v[8:9], v[8:9], v[124:125], v[192:193]
	v_add_f32_dpp v200, v200, v200 row_half_mirror row_mask:0xf bank_mask:0xf bound_ctrl:1
	s_nop 0
	v_add_f32_dpp v198, v198, v198 row_mirror row_mask:0xf bank_mask:0xf bound_ctrl:1
	s_nop 0
	v_add_f32_dpp v200, v200, v200 row_mirror row_mask:0xf bank_mask:0xf bound_ctrl:1
	v_pk_fma_f32 v[2:3], v[126:127], v[198:199], v[2:3] op_sel_hi:[1,0,1] neg_lo:[0,1,0] neg_hi:[0,1,0]
	v_pk_fma_f32 v[4:5], v[128:129], v[198:199], v[4:5] op_sel_hi:[1,0,1] neg_lo:[0,1,0] neg_hi:[0,1,0]
	v_pk_fma_f32 v[6:7], v[126:127], v[200:201], v[6:7] op_sel_hi:[1,0,1] neg_lo:[0,1,0] neg_hi:[0,1,0]
	v_pk_fma_f32 v[8:9], v[128:129], v[200:201], v[8:9] op_sel_hi:[1,0,1] neg_lo:[0,1,0] neg_hi:[0,1,0]
	v_pk_mul_f32 v[194:195], v[140:141], v[4:5]
	v_pk_mul_f32 v[196:197], v[140:141], v[8:9]
	v_pk_fma_f32 v[194:195], v[138:139], v[2:3], v[194:195]
	v_pk_fma_f32 v[196:197], v[138:139], v[6:7], v[196:197]
	v_add_f32_e32 v24, v194, v195
	v_add_f32_e32 v40, v196, v197
	s_waitcnt lgkmcnt(0)
	v_pk_mul_f32 v[176:177], v[2:3], v[166:167]
	v_pk_mul_f32 v[178:179], v[6:7], v[166:167]
	v_pk_fma_f32 v[176:177], v[4:5], v[168:169], v[176:177]
	v_pk_fma_f32 v[178:179], v[8:9], v[168:169], v[178:179]
	v_pk_mul_f32 v[180:181], v[162:163], v[174:175] op_sel_hi:[1,0]
	v_add_f32_e32 v198, v176, v177
	v_pk_mul_f32 v[190:191], v[162:163], v[174:175] op_sel:[0,1] op_sel_hi:[1,1]
	v_add_f32_e32 v200, v178, v179
	v_pk_mul_f32 v[188:189], v[164:165], v[174:175] op_sel_hi:[1,0]
	v_add_f32_dpp v198, v198, v198 quad_perm:[1,0,3,2] row_mask:0xf bank_mask:0xf bound_ctrl:1
	v_pk_mul_f32 v[192:193], v[164:165], v[174:175] op_sel:[0,1] op_sel_hi:[1,1]
	v_add_f32_dpp v200, v200, v200 quad_perm:[1,0,3,2] row_mask:0xf bank_mask:0xf bound_ctrl:1
	v_pk_fma_f32 v[2:3], v[2:3], v[154:155], v[180:181]
	v_add_f32_dpp v198, v198, v198 quad_perm:[2,3,0,1] row_mask:0xf bank_mask:0xf bound_ctrl:1
	v_pk_fma_f32 v[6:7], v[6:7], v[154:155], v[190:191]
	v_add_f32_dpp v200, v200, v200 quad_perm:[2,3,0,1] row_mask:0xf bank_mask:0xf bound_ctrl:1
	v_pk_fma_f32 v[4:5], v[4:5], v[156:157], v[188:189]
	v_add_f32_dpp v198, v198, v198 row_half_mirror row_mask:0xf bank_mask:0xf bound_ctrl:1
	v_pk_fma_f32 v[8:9], v[8:9], v[156:157], v[192:193]
	v_add_f32_dpp v200, v200, v200 row_half_mirror row_mask:0xf bank_mask:0xf bound_ctrl:1
	s_nop 0
	v_add_f32_dpp v198, v198, v198 row_mirror row_mask:0xf bank_mask:0xf bound_ctrl:1
	s_nop 0
	v_add_f32_dpp v200, v200, v200 row_mirror row_mask:0xf bank_mask:0xf bound_ctrl:1
	v_pk_fma_f32 v[2:3], v[158:159], v[198:199], v[2:3] op_sel_hi:[1,0,1] neg_lo:[0,1,0] neg_hi:[0,1,0]
	v_pk_fma_f32 v[4:5], v[160:161], v[198:199], v[4:5] op_sel_hi:[1,0,1] neg_lo:[0,1,0] neg_hi:[0,1,0]
	v_pk_fma_f32 v[6:7], v[158:159], v[200:201], v[6:7] op_sel_hi:[1,0,1] neg_lo:[0,1,0] neg_hi:[0,1,0]
	v_pk_fma_f32 v[8:9], v[160:161], v[200:201], v[8:9] op_sel_hi:[1,0,1] neg_lo:[0,1,0] neg_hi:[0,1,0]
	v_pk_mul_f32 v[194:195], v[172:173], v[4:5]
	v_pk_mul_f32 v[196:197], v[172:173], v[8:9]
	v_pk_fma_f32 v[194:195], v[170:171], v[2:3], v[194:195]
	v_pk_fma_f32 v[196:197], v[170:171], v[6:7], v[196:197]
	v_add_f32_e32 v25, v194, v195
	v_add_f32_e32 v41, v196, v197
	v_cndmask_b32_e64 v176, v10, v18, s[56:57]
	v_cndmask_b32_e64 v177, v18, v10, s[56:57]
	v_cndmask_b32_e64 v178, v11, v19, s[56:57]
	v_cndmask_b32_e64 v179, v19, v11, s[56:57]
	v_cndmask_b32_e64 v180, v12, v20, s[56:57]
	v_cndmask_b32_e64 v181, v20, v12, s[56:57]
	v_cndmask_b32_e64 v188, v13, v21, s[56:57]
	v_cndmask_b32_e64 v189, v21, v13, s[56:57]
	v_add_f32_dpp v190, v177, v176 row_mirror row_mask:0xf bank_mask:0xf bound_ctrl:1
	v_add_f32_dpp v191, v179, v178 row_mirror row_mask:0xf bank_mask:0xf bound_ctrl:1
	v_add_f32_dpp v192, v181, v180 row_mirror row_mask:0xf bank_mask:0xf bound_ctrl:1
	v_add_f32_dpp v193, v189, v188 row_mirror row_mask:0xf bank_mask:0xf bound_ctrl:1
	v_cndmask_b32_e64 v176, v14, v22, s[56:57]
	v_cndmask_b32_e64 v177, v22, v14, s[56:57]
	v_cndmask_b32_e64 v178, v15, v23, s[56:57]
	v_cndmask_b32_e64 v179, v23, v15, s[56:57]
	v_cndmask_b32_e64 v180, v16, v24, s[56:57]
	v_cndmask_b32_e64 v181, v24, v16, s[56:57]
	v_cndmask_b32_e64 v188, v17, v25, s[56:57]
	v_cndmask_b32_e64 v189, v25, v17, s[56:57]
	v_add_f32_dpp v194, v177, v176 row_mirror row_mask:0xf bank_mask:0xf bound_ctrl:1
	v_add_f32_dpp v195, v179, v178 row_mirror row_mask:0xf bank_mask:0xf bound_ctrl:1
	v_add_f32_dpp v196, v181, v180 row_mirror row_mask:0xf bank_mask:0xf bound_ctrl:1
	v_add_f32_dpp v197, v189, v188 row_mirror row_mask:0xf bank_mask:0xf bound_ctrl:1
	v_cndmask_b32_e64 v176, v190, v194, s[82:83]
	v_cndmask_b32_e64 v177, v194, v190, s[82:83]
	v_cndmask_b32_e64 v178, v191, v195, s[82:83]
	v_cndmask_b32_e64 v179, v195, v191, s[82:83]
	v_cndmask_b32_e64 v180, v192, v196, s[82:83]
	v_cndmask_b32_e64 v181, v196, v192, s[82:83]
	v_cndmask_b32_e64 v188, v193, v197, s[82:83]
	v_cndmask_b32_e64 v189, v197, v193, s[82:83]
	v_add_f32_dpp v202, v177, v176 row_half_mirror row_mask:0xf bank_mask:0xf bound_ctrl:1
	v_add_f32_dpp v203, v179, v178 row_half_mirror row_mask:0xf bank_mask:0xf bound_ctrl:1
	v_add_f32_dpp v204, v181, v180 row_half_mirror row_mask:0xf bank_mask:0xf bound_ctrl:1
	v_add_f32_dpp v205, v189, v188 row_half_mirror row_mask:0xf bank_mask:0xf bound_ctrl:1
	v_cndmask_b32_e64 v176, v202, v204, s[84:85]
	v_cndmask_b32_e64 v177, v204, v202, s[84:85]
	v_cndmask_b32_e64 v178, v203, v205, s[84:85]
	v_cndmask_b32_e64 v179, v205, v203, s[84:85]
	s_nop 1
	v_add_f32_dpp v210, v177, v176 quad_perm:[2,3,0,1] row_mask:0xf bank_mask:0xf bound_ctrl:1
	v_add_f32_dpp v211, v179, v178 quad_perm:[2,3,0,1] row_mask:0xf bank_mask:0xf bound_ctrl:1
	s_nop 0
	v_cndmask_b32_e64 v176, v210, v211, s[88:89]
	v_cndmask_b32_e64 v177, v211, v210, s[88:89]
	s_nop 1
	v_add_f32_dpp v212, v177, v176 quad_perm:[1,0,3,2] row_mask:0xf bank_mask:0xf bound_ctrl:1
	ds_write_b32 v44, v212 offset:2304
	v_cndmask_b32_e64 v176, v26, v34, s[56:57]
	v_cndmask_b32_e64 v177, v34, v26, s[56:57]
	v_cndmask_b32_e64 v178, v27, v35, s[56:57]
	v_cndmask_b32_e64 v179, v35, v27, s[56:57]
	v_cndmask_b32_e64 v180, v28, v36, s[56:57]
	v_cndmask_b32_e64 v181, v36, v28, s[56:57]
	v_cndmask_b32_e64 v188, v29, v37, s[56:57]
	v_cndmask_b32_e64 v189, v37, v29, s[56:57]
	v_add_f32_dpp v190, v177, v176 row_mirror row_mask:0xf bank_mask:0xf bound_ctrl:1
	v_add_f32_dpp v191, v179, v178 row_mirror row_mask:0xf bank_mask:0xf bound_ctrl:1
	v_add_f32_dpp v192, v181, v180 row_mirror row_mask:0xf bank_mask:0xf bound_ctrl:1
	v_add_f32_dpp v193, v189, v188 row_mirror row_mask:0xf bank_mask:0xf bound_ctrl:1
	v_cndmask_b32_e64 v176, v30, v38, s[56:57]
	v_cndmask_b32_e64 v177, v38, v30, s[56:57]
	v_cndmask_b32_e64 v178, v31, v39, s[56:57]
	v_cndmask_b32_e64 v179, v39, v31, s[56:57]
	v_cndmask_b32_e64 v180, v32, v40, s[56:57]
	v_cndmask_b32_e64 v181, v40, v32, s[56:57]
	v_cndmask_b32_e64 v188, v33, v41, s[56:57]
	v_cndmask_b32_e64 v189, v41, v33, s[56:57]
	v_add_f32_dpp v194, v177, v176 row_mirror row_mask:0xf bank_mask:0xf bound_ctrl:1
	v_add_f32_dpp v195, v179, v178 row_mirror row_mask:0xf bank_mask:0xf bound_ctrl:1
	v_add_f32_dpp v196, v181, v180 row_mirror row_mask:0xf bank_mask:0xf bound_ctrl:1
	v_add_f32_dpp v197, v189, v188 row_mirror row_mask:0xf bank_mask:0xf bound_ctrl:1
	v_cndmask_b32_e64 v176, v190, v194, s[82:83]
	v_cndmask_b32_e64 v177, v194, v190, s[82:83]
	v_cndmask_b32_e64 v178, v191, v195, s[82:83]
	v_cndmask_b32_e64 v179, v195, v191, s[82:83]
	v_cndmask_b32_e64 v180, v192, v196, s[82:83]
	v_cndmask_b32_e64 v181, v196, v192, s[82:83]
	v_cndmask_b32_e64 v188, v193, v197, s[82:83]
	v_cndmask_b32_e64 v189, v197, v193, s[82:83]
	v_add_f32_dpp v202, v177, v176 row_half_mirror row_mask:0xf bank_mask:0xf bound_ctrl:1
	v_add_f32_dpp v203, v179, v178 row_half_mirror row_mask:0xf bank_mask:0xf bound_ctrl:1
	v_add_f32_dpp v204, v181, v180 row_half_mirror row_mask:0xf bank_mask:0xf bound_ctrl:1
	v_add_f32_dpp v205, v189, v188 row_half_mirror row_mask:0xf bank_mask:0xf bound_ctrl:1
	v_cndmask_b32_e64 v176, v202, v204, s[84:85]
	v_cndmask_b32_e64 v177, v204, v202, s[84:85]
	v_cndmask_b32_e64 v178, v203, v205, s[84:85]
	v_cndmask_b32_e64 v179, v205, v203, s[84:85]
	s_nop 1
	v_add_f32_dpp v210, v177, v176 quad_perm:[2,3,0,1] row_mask:0xf bank_mask:0xf bound_ctrl:1
	v_add_f32_dpp v211, v179, v178 quad_perm:[2,3,0,1] row_mask:0xf bank_mask:0xf bound_ctrl:1
	s_nop 0
	v_cndmask_b32_e64 v176, v210, v211, s[88:89]
	v_cndmask_b32_e64 v177, v211, v210, s[88:89]
	s_nop 1
	v_add_f32_dpp v212, v177, v176 quad_perm:[1,0,3,2] row_mask:0xf bank_mask:0xf bound_ctrl:1
	ds_write_b32 v44, v212 offset:2320
	v_xor_b32_e32 v42, 0xc000, v42
	v_xor_b32_e32 v43, 0xc000, v43
	v_xor_b32_e32 v44, 0x2000, v44
	s_branch .Lrc_join
.Lrc_stage:
	s_cmp_eq_u32 s2, 0
	s_cbranch_scc1 .Lrc_fl_done
	s_add_u32 s30, s2, -1
	s_lshl_b32 s26, s30, 5
	s_movk_i32 s27, 0xff
	s_cmp_lt_u32 s26, 0x100
	s_cselect_b32 s27, s27, 0x11ff
	s_sub_u32 s27, s27, s26
	s_cmp_eq_u32 s35, 0
	s_cselect_b32 s28, s26, s27
	ds_read_b128 v[130:133], v125
	v_add_u32_e32 v134, s28, v124
	s_cmp_lt_u32 s30, 8
	s_cbranch_scc0 .Lrc_fl_lat_p
	v_add_u32_e32 v135, s44, v134
	s_branch .Lrc_fl_row_p
.Lrc_fl_lat_p:
	v_subrev_u32_e32 v134, 0x100, v134
	s_cmp_eq_u32 s36, 0
	s_cbranch_scc1 .Lrc_fl_even_p
	v_and_b32_e32 v136, 63, v134
	v_lshrrev_b32_e32 v137, 6, v134
	v_lshl_or_b32 v134, v136, 6, v137
.Lrc_fl_even_p:
	v_add_u32_e32 v135, s45, v134
.Lrc_fl_row_p:
	v_mov_b32_e32 v136, 0x1800
	v_mad_u32_u24 v135, v135, v136, v126
	s_waitcnt lgkmcnt(0)
	v_cvt_pk_bf16_f32 v138, v130, v131
	v_cvt_pk_bf16_f32 v139, v132, v133
	global_store_dwordx2 v135, v[138:139], s[16:17]
.Lrc_fl_done:
	s_bitcmp1_b32 s2, 0
	s_cbranch_scc1 .Lrc_par1
	s_cmp_lt_u32 s2, 134
	s_cbranch_scc0 .Lrc_noload0
	s_add_u32 s30, s2, 2
	s_lshl_b32 s26, s30, 5
	s_movk_i32 s27, 0xff
	s_cmp_lt_u32 s26, 0x100
	s_cselect_b32 s27, s27, 0x11ff
	s_sub_u32 s27, s27, s26
	s_cmp_eq_u32 s35, 0
	s_cselect_b32 s29, s26, s27
	s_mul_i32 s29, s29, 0x300
	v_add_u32_e32 v127, s29, v122
	v_add_u32_e32 v128, s92, v127
	global_load_dwordx4 v[2:5], v128, s[18:19]
	v_add_u32_e32 v128, s93, v127
	global_load_dwordx4 v[6:9], v128, s[18:19]
	v_add_u32_e32 v128, s94, v127
	global_load_dwordx4 v[10:13], v128, s[18:19]
	v_add_u32_e32 v128, 0x3300000, v127
	global_load_dwordx4 v[14:17], v128, s[18:19]
	v_mov_b32_e32 v128, v127
	global_load_dwordx4 v[18:21], v128, s[18:19]
	v_add_u32_e32 v128, 0x1980000, v127
	global_load_dwordx4 v[22:25], v128, s[18:19]
	s_waitcnt vmcnt(6)
	v_add_u32_e32 v129, s25, v123
	v_lshlrev_b32_e32 v26, 16, v154
	v_and_b32_e32 v27, 0xffff0000, v154
	v_lshlrev_b32_e32 v28, 16, v155
	v_and_b32_e32 v29, 0xffff0000, v155
	v_lshlrev_b32_e32 v30, 16, v156
	v_and_b32_e32 v31, 0xffff0000, v156
	v_lshlrev_b32_e32 v32, 16, v157
	v_and_b32_e32 v33, 0xffff0000, v157
	v_sub_f32_e32 v26, 1.0, v26
	v_sub_f32_e32 v27, 1.0, v27
	v_sub_f32_e32 v28, 1.0, v28
	v_sub_f32_e32 v29, 1.0, v29
	v_sub_f32_e32 v30, 1.0, v30
	v_sub_f32_e32 v31, 1.0, v31
	v_sub_f32_e32 v32, 1.0, v32
	v_sub_f32_e32 v33, 1.0, v33
	ds_write_b128 v129, v[26:29] offset:0
	ds_write_b128 v129, v[30:33] offset:16
	v_lshlrev_b32_e32 v34, 16, v158
	v_and_b32_e32 v35, 0xffff0000, v158
	v_lshlrev_b32_e32 v36, 16, v159
	v_and_b32_e32 v37, 0xffff0000, v159
	v_lshlrev_b32_e32 v38, 16, v160
	v_and_b32_e32 v39, 0xffff0000, v160
	v_lshlrev_b32_e32 v40, 16, v161
	v_and_b32_e32 v41, 0xffff0000, v161
	ds_write_b128 v129, v[34:37] offset:256
	ds_write_b128 v129, v[38:41] offset:272
	v_lshlrev_b32_e32 v26, 16, v162
	v_and_b32_e32 v27, 0xffff0000, v162
	v_lshlrev_b32_e32 v28, 16, v163
	v_and_b32_e32 v29, 0xffff0000, v163
	v_lshlrev_b32_e32 v30, 16, v164
	v_and_b32_e32 v31, 0xffff0000, v164
	v_lshlrev_b32_e32 v32, 16, v165
	v_and_b32_e32 v33, 0xffff0000, v165
	ds_write_b128 v129, v[26:29] offset:512
	ds_write_b128 v129, v[30:33] offset:528
	v_lshlrev_b32_e32 v34, 16, v166
	v_and_b32_e32 v35, 0xffff0000, v166
	v_lshlrev_b32_e32 v36, 16, v167
	v_and_b32_e32 v37, 0xffff0000, v167
	v_lshlrev_b32_e32 v38, 16, v168
	v_and_b32_e32 v39, 0xffff0000, v168
	v_lshlrev_b32_e32 v40, 16, v169
	v_and_b32_e32 v41, 0xffff0000, v169
	ds_write_b128 v129, v[34:37] offset:768
	ds_write_b128 v129, v[38:41] offset:784
	v_lshlrev_b32_e32 v26, 16, v170
	v_and_b32_e32 v27, 0xffff0000, v170
	v_lshlrev_b32_e32 v28, 16, v171
	v_and_b32_e32 v29, 0xffff0000, v171
	v_lshlrev_b32_e32 v30, 16, v172
	v_and_b32_e32 v31, 0xffff0000, v172
	v_lshlrev_b32_e32 v32, 16, v173
	v_and_b32_e32 v33, 0xffff0000, v173
	ds_write_b128 v129, v[26:29] offset:1024
	ds_write_b128 v129, v[30:33] offset:1040
	v_lshlrev_b32_e32 v34, 16, v174
	v_and_b32_e32 v35, 0xffff0000, v174
	v_lshlrev_b32_e32 v36, 16, v175
	v_and_b32_e32 v37, 0xffff0000, v175
	v_lshlrev_b32_e32 v38, 16, v176
	v_and_b32_e32 v39, 0xffff0000, v176
	v_lshlrev_b32_e32 v40, 16, v177
	v_and_b32_e32 v41, 0xffff0000, v177
	ds_write_b128 v129, v[34:37] offset:1280
	ds_write_b128 v129, v[38:41] offset:1296
	s_branch .Lrc_nostore
.Lrc_noload0:
	s_cmp_lt_u32 s2, 135
	s_cbranch_scc0 .Lrc_nostore
	s_waitcnt vmcnt(0)
	v_add_u32_e32 v129, s25, v123
	v_lshlrev_b32_e32 v26, 16, v154
	v_and_b32_e32 v27, 0xffff0000, v154
	v_lshlrev_b32_e32 v28, 16, v155
	v_and_b32_e32 v29, 0xffff0000, v155
	v_lshlrev_b32_e32 v30, 16, v156
	v_and_b32_e32 v31, 0xffff0000, v156
	v_lshlrev_b32_e32 v32, 16, v157
	v_and_b32_e32 v33, 0xffff0000, v157
	v_sub_f32_e32 v26, 1.0, v26
	v_sub_f32_e32 v27, 1.0, v27
	v_sub_f32_e32 v28, 1.0, v28
	v_sub_f32_e32 v29, 1.0, v29
	v_sub_f32_e32 v30, 1.0, v30
	v_sub_f32_e32 v31, 1.0, v31
	v_sub_f32_e32 v32, 1.0, v32
	v_sub_f32_e32 v33, 1.0, v33
	ds_write_b128 v129, v[26:29] offset:0
	ds_write_b128 v129, v[30:33] offset:16
	v_lshlrev_b32_e32 v34, 16, v158
	v_and_b32_e32 v35, 0xffff0000, v158
	v_lshlrev_b32_e32 v36, 16, v159
	v_and_b32_e32 v37, 0xffff0000, v159
	v_lshlrev_b32_e32 v38, 16, v160
	v_and_b32_e32 v39, 0xffff0000, v160
	v_lshlrev_b32_e32 v40, 16, v161
	v_and_b32_e32 v41, 0xffff0000, v161
	ds_write_b128 v129, v[34:37] offset:256
	ds_write_b128 v129, v[38:41] offset:272
	v_lshlrev_b32_e32 v26, 16, v162
	v_and_b32_e32 v27, 0xffff0000, v162
	v_lshlrev_b32_e32 v28, 16, v163
	v_and_b32_e32 v29, 0xffff0000, v163
	v_lshlrev_b32_e32 v30, 16, v164
	v_and_b32_e32 v31, 0xffff0000, v164
	v_lshlrev_b32_e32 v32, 16, v165
	v_and_b32_e32 v33, 0xffff0000, v165
	ds_write_b128 v129, v[26:29] offset:512
	ds_write_b128 v129, v[30:33] offset:528
	v_lshlrev_b32_e32 v34, 16, v166
	v_and_b32_e32 v35, 0xffff0000, v166
	v_lshlrev_b32_e32 v36, 16, v167
	v_and_b32_e32 v37, 0xffff0000, v167
	v_lshlrev_b32_e32 v38, 16, v168
	v_and_b32_e32 v39, 0xffff0000, v168
	v_lshlrev_b32_e32 v40, 16, v169
	v_and_b32_e32 v41, 0xffff0000, v169
	ds_write_b128 v129, v[34:37] offset:768
	ds_write_b128 v129, v[38:41] offset:784
	v_lshlrev_b32_e32 v26, 16, v170
	v_and_b32_e32 v27, 0xffff0000, v170
	v_lshlrev_b32_e32 v28, 16, v171
	v_and_b32_e32 v29, 0xffff0000, v171
	v_lshlrev_b32_e32 v30, 16, v172
	v_and_b32_e32 v31, 0xffff0000, v172
	v_lshlrev_b32_e32 v32, 16, v173
	v_and_b32_e32 v33, 0xffff0000, v173
	ds_write_b128 v129, v[26:29] offset:1024
	ds_write_b128 v129, v[30:33] offset:1040
	v_lshlrev_b32_e32 v34, 16, v174
	v_and_b32_e32 v35, 0xffff0000, v174
	v_lshlrev_b32_e32 v36, 16, v175
	v_and_b32_e32 v37, 0xffff0000, v175
	v_lshlrev_b32_e32 v38, 16, v176
	v_and_b32_e32 v39, 0xffff0000, v176
	v_lshlrev_b32_e32 v40, 16, v177
	v_and_b32_e32 v41, 0xffff0000, v177
	ds_write_b128 v129, v[34:37] offset:1280
	ds_write_b128 v129, v[38:41] offset:1296
	s_branch .Lrc_nostore
.Lrc_par1:
	s_cmp_lt_u32 s2, 134
	s_cbranch_scc0 .Lrc_noload1
	s_add_u32 s30, s2, 2
	s_lshl_b32 s26, s30, 5
	s_movk_i32 s27, 0xff
	s_cmp_lt_u32 s26, 0x100
	s_cselect_b32 s27, s27, 0x11ff
	s_sub_u32 s27, s27, s26
	s_cmp_eq_u32 s35, 0
	s_cselect_b32 s29, s26, s27
	s_mul_i32 s29, s29, 0x300
	v_add_u32_e32 v127, s29, v122
	v_add_u32_e32 v128, s92, v127
	global_load_dwordx4 v[154:157], v128, s[18:19]
	v_add_u32_e32 v128, s93, v127
	global_load_dwordx4 v[158:161], v128, s[18:19]
	v_add_u32_e32 v128, s94, v127
	global_load_dwordx4 v[162:165], v128, s[18:19]
	v_add_u32_e32 v128, 0x3300000, v127
	global_load_dwordx4 v[166:169], v128, s[18:19]
	v_mov_b32_e32 v128, v127
	global_load_dwordx4 v[170:173], v128, s[18:19]
	v_add_u32_e32 v128, 0x1980000, v127
	global_load_dwordx4 v[174:177], v128, s[18:19]
	s_waitcnt vmcnt(6)
	v_add_u32_e32 v129, s25, v123
	v_lshlrev_b32_e32 v26, 16, v2
	v_and_b32_e32 v27, 0xffff0000, v2
	v_lshlrev_b32_e32 v28, 16, v3
	v_and_b32_e32 v29, 0xffff0000, v3
	v_lshlrev_b32_e32 v30, 16, v4
	v_and_b32_e32 v31, 0xffff0000, v4
	v_lshlrev_b32_e32 v32, 16, v5
	v_and_b32_e32 v33, 0xffff0000, v5
	v_sub_f32_e32 v26, 1.0, v26
	v_sub_f32_e32 v27, 1.0, v27
	v_sub_f32_e32 v28, 1.0, v28
	v_sub_f32_e32 v29, 1.0, v29
	v_sub_f32_e32 v30, 1.0, v30
	v_sub_f32_e32 v31, 1.0, v31
	v_sub_f32_e32 v32, 1.0, v32
	v_sub_f32_e32 v33, 1.0, v33
	ds_write_b128 v129, v[26:29] offset:0
	ds_write_b128 v129, v[30:33] offset:16
	v_lshlrev_b32_e32 v34, 16, v6
	v_and_b32_e32 v35, 0xffff0000, v6
	v_lshlrev_b32_e32 v36, 16, v7
	v_and_b32_e32 v37, 0xffff0000, v7
	v_lshlrev_b32_e32 v38, 16, v8
	v_and_b32_e32 v39, 0xffff0000, v8
	v_lshlrev_b32_e32 v40, 16, v9
	v_and_b32_e32 v41, 0xffff0000, v9
	ds_write_b128 v129, v[34:37] offset:256
	ds_write_b128 v129, v[38:41] offset:272
	v_lshlrev_b32_e32 v26, 16, v10
	v_and_b32_e32 v27, 0xffff0000, v10
	v_lshlrev_b32_e32 v28, 16, v11
	v_and_b32_e32 v29, 0xffff0000, v11
	v_lshlrev_b32_e32 v30, 16, v12
	v_and_b32_e32 v31, 0xffff0000, v12
	v_lshlrev_b32_e32 v32, 16, v13
	v_and_b32_e32 v33, 0xffff0000, v13
	ds_write_b128 v129, v[26:29] offset:512
	ds_write_b128 v129, v[30:33] offset:528
	v_lshlrev_b32_e32 v34, 16, v14
	v_and_b32_e32 v35, 0xffff0000, v14
	v_lshlrev_b32_e32 v36, 16, v15
	v_and_b32_e32 v37, 0xffff0000, v15
	v_lshlrev_b32_e32 v38, 16, v16
	v_and_b32_e32 v39, 0xffff0000, v16
	v_lshlrev_b32_e32 v40, 16, v17
	v_and_b32_e32 v41, 0xffff0000, v17
	ds_write_b128 v129, v[34:37] offset:768
	ds_write_b128 v129, v[38:41] offset:784
	v_lshlrev_b32_e32 v26, 16, v18
	v_and_b32_e32 v27, 0xffff0000, v18
	v_lshlrev_b32_e32 v28, 16, v19
	v_and_b32_e32 v29, 0xffff0000, v19
	v_lshlrev_b32_e32 v30, 16, v20
	v_and_b32_e32 v31, 0xffff0000, v20
	v_lshlrev_b32_e32 v32, 16, v21
	v_and_b32_e32 v33, 0xffff0000, v21
	ds_write_b128 v129, v[26:29] offset:1024
	ds_write_b128 v129, v[30:33] offset:1040
	v_lshlrev_b32_e32 v34, 16, v22
	v_and_b32_e32 v35, 0xffff0000, v22
	v_lshlrev_b32_e32 v36, 16, v23
	v_and_b32_e32 v37, 0xffff0000, v23
	v_lshlrev_b32_e32 v38, 16, v24
	v_and_b32_e32 v39, 0xffff0000, v24
	v_lshlrev_b32_e32 v40, 16, v25
	v_and_b32_e32 v41, 0xffff0000, v25
	ds_write_b128 v129, v[34:37] offset:1280
	ds_write_b128 v129, v[38:41] offset:1296
	s_branch .Lrc_nostore
.Lrc_noload1:
	s_cmp_lt_u32 s2, 135
	s_cbranch_scc0 .Lrc_nostore
	s_waitcnt vmcnt(0)
	v_add_u32_e32 v129, s25, v123
	v_lshlrev_b32_e32 v26, 16, v2
	v_and_b32_e32 v27, 0xffff0000, v2
	v_lshlrev_b32_e32 v28, 16, v3
	v_and_b32_e32 v29, 0xffff0000, v3
	v_lshlrev_b32_e32 v30, 16, v4
	v_and_b32_e32 v31, 0xffff0000, v4
	v_lshlrev_b32_e32 v32, 16, v5
	v_and_b32_e32 v33, 0xffff0000, v5
	v_sub_f32_e32 v26, 1.0, v26
	v_sub_f32_e32 v27, 1.0, v27
	v_sub_f32_e32 v28, 1.0, v28
	v_sub_f32_e32 v29, 1.0, v29
	v_sub_f32_e32 v30, 1.0, v30
	v_sub_f32_e32 v31, 1.0, v31
	v_sub_f32_e32 v32, 1.0, v32
	v_sub_f32_e32 v33, 1.0, v33
	ds_write_b128 v129, v[26:29] offset:0
	ds_write_b128 v129, v[30:33] offset:16
	v_lshlrev_b32_e32 v34, 16, v6
	v_and_b32_e32 v35, 0xffff0000, v6
	v_lshlrev_b32_e32 v36, 16, v7
	v_and_b32_e32 v37, 0xffff0000, v7
	v_lshlrev_b32_e32 v38, 16, v8
	v_and_b32_e32 v39, 0xffff0000, v8
	v_lshlrev_b32_e32 v40, 16, v9
	v_and_b32_e32 v41, 0xffff0000, v9
	ds_write_b128 v129, v[34:37] offset:256
	ds_write_b128 v129, v[38:41] offset:272
	v_lshlrev_b32_e32 v26, 16, v10
	v_and_b32_e32 v27, 0xffff0000, v10
	v_lshlrev_b32_e32 v28, 16, v11
	v_and_b32_e32 v29, 0xffff0000, v11
	v_lshlrev_b32_e32 v30, 16, v12
	v_and_b32_e32 v31, 0xffff0000, v12
	v_lshlrev_b32_e32 v32, 16, v13
	v_and_b32_e32 v33, 0xffff0000, v13
	ds_write_b128 v129, v[26:29] offset:512
	ds_write_b128 v129, v[30:33] offset:528
	v_lshlrev_b32_e32 v34, 16, v14
	v_and_b32_e32 v35, 0xffff0000, v14
	v_lshlrev_b32_e32 v36, 16, v15
	v_and_b32_e32 v37, 0xffff0000, v15
	v_lshlrev_b32_e32 v38, 16, v16
	v_and_b32_e32 v39, 0xffff0000, v16
	v_lshlrev_b32_e32 v40, 16, v17
	v_and_b32_e32 v41, 0xffff0000, v17
	ds_write_b128 v129, v[34:37] offset:768
	ds_write_b128 v129, v[38:41] offset:784
	v_lshlrev_b32_e32 v26, 16, v18
	v_and_b32_e32 v27, 0xffff0000, v18
	v_lshlrev_b32_e32 v28, 16, v19
	v_and_b32_e32 v29, 0xffff0000, v19
	v_lshlrev_b32_e32 v30, 16, v20
	v_and_b32_e32 v31, 0xffff0000, v20
	v_lshlrev_b32_e32 v32, 16, v21
	v_and_b32_e32 v33, 0xffff0000, v21
	ds_write_b128 v129, v[26:29] offset:1024
	ds_write_b128 v129, v[30:33] offset:1040
	v_lshlrev_b32_e32 v34, 16, v22
	v_and_b32_e32 v35, 0xffff0000, v22
	v_lshlrev_b32_e32 v36, 16, v23
	v_and_b32_e32 v37, 0xffff0000, v23
	v_lshlrev_b32_e32 v38, 16, v24
	v_and_b32_e32 v39, 0xffff0000, v24
	v_lshlrev_b32_e32 v40, 16, v25
	v_and_b32_e32 v41, 0xffff0000, v25
	ds_write_b128 v129, v[34:37] offset:1280
	ds_write_b128 v129, v[38:41] offset:1296
.Lrc_nostore:
	v_xor_b32_e32 v125, 0x2000, v125
	s_xor_b32 s25, s25, 0xc000
.Lrc_join:
	s_waitcnt lgkmcnt(0)
	s_barrier
	s_add_u32 s2, s2, 1
	s_cmp_lt_u32 s2, 136
	s_cbranch_scc1 .Lrc_chunk
	s_cmp_gt_u32 s34, 3
	s_cbranch_scc0 .Lrc_exit
	s_add_u32 s30, s2, -1
	s_lshl_b32 s26, s30, 5
	s_movk_i32 s27, 0xff
	s_cmp_lt_u32 s26, 0x100
	s_cselect_b32 s27, s27, 0x11ff
	s_sub_u32 s27, s27, s26
	s_cmp_eq_u32 s35, 0
	s_cselect_b32 s28, s26, s27
	ds_read_b128 v[130:133], v125
	v_add_u32_e32 v134, s28, v124
	s_cmp_lt_u32 s30, 8
	s_cbranch_scc0 .Lrc_fl_lat_z
	v_add_u32_e32 v135, s44, v134
	s_branch .Lrc_fl_row_z

.Lrc_exit:
	s_setprio 0
	v_readlane_b32 s94, v254, 22
	v_readlane_b32 s95, v254, 23
	s_mov_b32 s92, 0x10000
	s_mov_b32 s93, 0x14000
	s_movk_i32 s88, 0x2ff
	s_movk_i32 s89, 0x600
	s_movk_i32 s52, 0x11ff
	s_movk_i32 s56, 0x43
	s_branch .LBB0_239
